# GEMM mainloops: s_setprio flips moved across the phase barriers, out of the MFMA-paced segment
# speedup vs baseline: 1.0058x; 1.0058x over previous
; #define PG8_STAGE(bufoff, gbase, voff) do { _Pragma("unroll") for (int _i = 0; _i < 2; ++_i) \
;         __builtin_amdgcn_global_load_lds((const unsigned*)((const char*)(gbase) + (voff)[_i]), (LAS unsigned*)(lds + (bufoff) + ldsw + _i * 8192), 16, 0, 0); } while (0)
; #define PG8_LDA(dst, b, h) do { _Pragma("unroll") for (int m = 0; m < 4; ++m) _Pragma("unroll") for (int k = 0; k < 2; ++k) dst[m][k] = *(const LAS bf16x8*)(lds + PG8_SA(b, h) + aoff + m * 2048 + k * 1024); } while (0)
; #define PG8_LDB(dst, b, h) do { _Pragma("unroll") for (int n = 0; n < 2; ++n) _Pragma("unroll") for (int k = 0; k < 2; ++k) dst[n][k] = *(const LAS bf16x8*)(lds + PG8_SB(b, h) + boff + n * 2048 + k * 1024); } while (0)
; #define PG8_MMA(ai, bj, At, Bt) do { __builtin_amdgcn_s_setprio(1); _Pragma("unroll") for (int m = 0; m < 4; ++m) _Pragma("unroll") for (int n = 0; n < 2; ++n) _Pragma("unroll") for (int k = 0; k < 2; ++k) \
;         acc[ai][bj][m][n] = __builtin_amdgcn_mfma_f32_16x16x32_bf16(Bt[n][k], At[m][k], acc[ai][bj][m][n], 0, 0, 0); __builtin_amdgcn_s_setprio(0); } while (0)
; #define PG8_WAIT_V(n) asm volatile("s_waitcnt vmcnt(" #n ")" ::: "memory")
; #define PG8_WAIT_L(n) asm volatile("s_waitcnt lgkmcnt(" #n ")" ::: "memory")
; #define PG8_BAR __builtin_amdgcn_s_barrier()
; #define PG8_SCHED __builtin_amdgcn_sched_barrier(0)
; template <class Epi, class Sched>
; __device__ __forceinline__ void gemm_phase(LAS unsigned char* lds, const Gemm g, const Sched S, const Epi E, const int tid) {
;     ...
;         for (int t = 0; t < nt; t += 2) {
;             const bool last = (t == nt - 2);
;             const char* a1 = cA + (size_t)(t + 1) * kstep;
;             const char* a2 = last ? nA : cA + (size_t)(t + 2) * kstep; const char* b2 = last ? nB : cB + (size_t)(t + 2) * kstep;
;             const char* a3 = a2 + kstep; const char* b3 = b2 + kstep;
;             PG8_LDB(B0, 0, 0); PG8_LDB(B1, 0, 1); PG8_SCHED; PG8_LDA(At, 0, 0); PG8_STAGE(PG8_SA(1, 1), a1 + hstepA, voffA);
;             PG8_WAIT_V(8); PG8_WAIT_L(0); PG8_BAR; PG8_MMA(0, 0, At, B0); PG8_MMA(0, 1, At, B1); PG8_BAR; PG8_SCHED;
;             PG8_LDA(At, 0, 1); PG8_STAGE(PG8_SB(0, 0), b2, voffB); PG8_STAGE(PG8_SB(0, 1), b2 + hstepB, voffB); PG8_STAGE(PG8_SA(0, 0), a2, voffA);
;             PG8_WAIT_V(8); PG8_WAIT_L(0); PG8_BAR; PG8_MMA(1, 0, At, B0); PG8_MMA(1, 1, At, B1); PG8_BAR; PG8_SCHED;
.LBB0_299:
	s_add_u32 s10, s22, 0xfffc0080
	s_addc_u32 s11, s23, -1
	s_add_i32 s44, 0, 0x10000
	s_cmp_eq_u32 vcc_hi, 28
	s_cselect_b32 s29, s93, s11
	s_cselect_b32 s28, s94, s10
	v_add_u32_e32 v154, s44, v167
	s_cselect_b32 s27, s95, vcc_lo
	s_cselect_b32 s26, s96, s97
	s_add_i32 s45, 0, 0x14000
	ds_read_b128 v[98:101], v154
	ds_read_b128 v[102:105], v154 offset:1024
	ds_read_b128 v[150:153], v154 offset:2048
	ds_read_b128 v[180:183], v154 offset:3072
	v_add_u32_e32 v154, s45, v167
	ds_read_b128 v[184:187], v154
	ds_read_b128 v[188:191], v154 offset:1024
	ds_read_b128 v[192:195], v154 offset:2048
	ds_read_b128 v[196:199], v154 offset:3072
	v_lshl_add_u64 v[154:155], s[22:23], 0, v[148:149]
	s_add_i32 m0, s47, 0xc000
	ds_read_b128 v[200:203], v179
	ds_read_b128 v[204:207], v179 offset:1024
	ds_read_b128 v[208:211], v179 offset:2048
	ds_read_b128 v[212:215], v179 offset:3072
	ds_read_b128 v[216:219], v179 offset:4096
	ds_read_b128 v[220:223], v179 offset:5120
	ds_read_b128 v[224:227], v179 offset:6144
	ds_read_b128 v[228:231], v179 offset:7168
	global_load_lds_dwordx4 v[154:155], off
	v_lshl_add_u64 v[154:155], s[22:23], 0, v[146:147]
	s_add_i32 m0, s47, 0xe000
	s_nop 0
	global_load_lds_dwordx4 v[154:155], off
	s_waitcnt vmcnt(8)
	s_waitcnt lgkmcnt(0)
	s_setprio 1
	s_barrier
	v_mfma_f32_16x16x32_bf16 v[134:137], v[98:101], v[200:203], v[134:137]
	v_mfma_f32_16x16x32_bf16 v[130:133], v[150:153], v[200:203], v[130:133]
	v_mfma_f32_16x16x32_bf16 v[126:129], v[98:101], v[208:211], v[126:129]
	v_mfma_f32_16x16x32_bf16 v[122:125], v[150:153], v[208:211], v[122:125]
	v_mfma_f32_16x16x32_bf16 v[118:121], v[98:101], v[216:219], v[118:121]
	v_mfma_f32_16x16x32_bf16 v[114:117], v[150:153], v[216:219], v[114:117]
	v_mfma_f32_16x16x32_bf16 v[110:113], v[98:101], v[224:227], v[110:113]
	v_mfma_f32_16x16x32_bf16 v[106:109], v[150:153], v[224:227], v[106:109]
	v_mfma_f32_16x16x32_bf16 v[134:137], v[102:105], v[204:207], v[134:137]
	v_mfma_f32_16x16x32_bf16 v[130:133], v[180:183], v[204:207], v[130:133]
	v_mfma_f32_16x16x32_bf16 v[126:129], v[102:105], v[212:215], v[126:129]
	v_mfma_f32_16x16x32_bf16 v[122:125], v[180:183], v[212:215], v[122:125]
	v_mfma_f32_16x16x32_bf16 v[118:121], v[102:105], v[220:223], v[118:121]
	v_mfma_f32_16x16x32_bf16 v[114:117], v[180:183], v[220:223], v[114:117]
	v_mfma_f32_16x16x32_bf16 v[110:113], v[102:105], v[228:231], v[110:113]
	v_mfma_f32_16x16x32_bf16 v[106:109], v[180:183], v[228:231], v[106:109]
	v_mfma_f32_16x16x32_bf16 v[62:65], v[184:187], v[200:203], v[62:65]
	v_mfma_f32_16x16x32_bf16 v[58:61], v[192:195], v[200:203], v[58:61]
	v_mfma_f32_16x16x32_bf16 v[54:57], v[184:187], v[208:211], v[54:57]
	v_mfma_f32_16x16x32_bf16 v[50:53], v[192:195], v[208:211], v[50:53]
	v_mfma_f32_16x16x32_bf16 v[46:49], v[184:187], v[216:219], v[46:49]
	v_mfma_f32_16x16x32_bf16 v[42:45], v[192:195], v[216:219], v[42:45]
	v_mfma_f32_16x16x32_bf16 v[38:41], v[184:187], v[224:227], v[38:41]
	v_mfma_f32_16x16x32_bf16 v[34:37], v[192:195], v[224:227], v[34:37]
	v_mfma_f32_16x16x32_bf16 v[62:65], v[188:191], v[204:207], v[62:65]
	v_mfma_f32_16x16x32_bf16 v[58:61], v[196:199], v[204:207], v[58:61]
	v_mfma_f32_16x16x32_bf16 v[54:57], v[188:191], v[212:215], v[54:57]
	v_mfma_f32_16x16x32_bf16 v[50:53], v[196:199], v[212:215], v[50:53]
	v_mfma_f32_16x16x32_bf16 v[46:49], v[188:191], v[220:223], v[46:49]
	v_mfma_f32_16x16x32_bf16 v[42:45], v[196:199], v[220:223], v[42:45]
	v_mfma_f32_16x16x32_bf16 v[38:41], v[188:191], v[228:231], v[38:41]
	v_mfma_f32_16x16x32_bf16 v[34:37], v[196:199], v[228:231], v[34:37]
	s_barrier
	s_setprio 0
	s_add_i32 s10, s44, s46
	v_lshl_add_u64 v[154:155], s[26:27], 0, v[142:143]
	s_mov_b32 m0, s10
	ds_read_b128 v[200:203], v179 offset:16384
	ds_read_b128 v[204:207], v179 offset:17408
	ds_read_b128 v[208:211], v179 offset:18432
	ds_read_b128 v[212:215], v179 offset:19456
	ds_read_b128 v[216:219], v179 offset:20480
	ds_read_b128 v[220:223], v179 offset:21504
	ds_read_b128 v[224:227], v179 offset:22528
	ds_read_b128 v[228:231], v179 offset:23552
	global_load_lds_dwordx4 v[154:155], off
	s_add_i32 m0, s10, 0x2000
	s_add_u32 s10, s26, 0x80000
	v_lshl_add_u64 v[232:233], s[26:27], 0, v[138:139]
	s_addc_u32 s11, s27, 0
	s_add_i32 s45, s45, s46
	global_load_lds_dwordx4 v[232:233], off
	v_lshl_add_u64 v[234:235], s[10:11], 0, v[142:143]
	s_mov_b32 m0, s45
	v_lshl_add_u64 v[246:247], s[28:29], 0, v[140:141]
	global_load_lds_dwordx4 v[234:235], off
	v_lshl_add_u64 v[234:235], s[10:11], 0, v[138:139]
	s_add_i32 m0, s45, 0x2000
	s_nop 0
	global_load_lds_dwordx4 v[234:235], off
	v_lshl_add_u64 v[234:235], s[28:29], 0, v[144:145]
	s_mov_b32 m0, s47
	s_nop 0
	global_load_lds_dwordx4 v[234:235], off
	s_mov_b32 m0, s48
	s_nop 0
	global_load_lds_dwordx4 v[246:247], off
	s_waitcnt vmcnt(8)
	s_waitcnt lgkmcnt(0)
	s_setprio 1
	s_barrier
; #define PG8_STAGE(bufoff, gbase, voff) do { _Pragma("unroll") for (int _i = 0; _i < 2; ++_i) \
;         __builtin_amdgcn_global_load_lds((const unsigned*)((const char*)(gbase) + (voff)[_i]), (LAS unsigned*)(lds + (bufoff) + ldsw + _i * 8192), 16, 0, 0); } while (0)
; #define PG8_LDA(dst, b, h) do { _Pragma("unroll") for (int m = 0; m < 4; ++m) _Pragma("unroll") for (int k = 0; k < 2; ++k) dst[m][k] = *(const LAS bf16x8*)(lds + PG8_SA(b, h) + aoff + m * 2048 + k * 1024); } while (0)
; #define PG8_LDB(dst, b, h) do { _Pragma("unroll") for (int n = 0; n < 2; ++n) _Pragma("unroll") for (int k = 0; k < 2; ++k) dst[n][k] = *(const LAS bf16x8*)(lds + PG8_SB(b, h) + boff + n * 2048 + k * 1024); } while (0)
; #define PG8_MMA(ai, bj, At, Bt) do { __builtin_amdgcn_s_setprio(1); _Pragma("unroll") for (int m = 0; m < 4; ++m) _Pragma("unroll") for (int n = 0; n < 2; ++n) _Pragma("unroll") for (int k = 0; k < 2; ++k) \
;         acc[ai][bj][m][n] = __builtin_amdgcn_mfma_f32_16x16x32_bf16(Bt[n][k], At[m][k], acc[ai][bj][m][n], 0, 0, 0); __builtin_amdgcn_s_setprio(0); } while (0)
; #define PG8_WAIT_V(n) asm volatile("s_waitcnt vmcnt(" #n ")" ::: "memory")
; #define PG8_WAIT_L(n) asm volatile("s_waitcnt lgkmcnt(" #n ")" ::: "memory")
; #define PG8_BAR __builtin_amdgcn_s_barrier()
; #define PG8_SCHED __builtin_amdgcn_sched_barrier(0)
; template <class Epi, class Sched>
; __device__ __forceinline__ void gemm_phase(LAS unsigned char* lds, const Gemm g, const Sched S, const Epi E, const int tid) {
;     ...
;             PG8_WAIT_V(8); PG8_WAIT_L(0); PG8_BAR; PG8_MMA(1, 0, At, B0); PG8_MMA(1, 1, At, B1); PG8_BAR; PG8_SCHED;
;             PG8_LDB(B0, 1, 0); PG8_LDB(B1, 1, 1); PG8_SCHED; PG8_LDA(At, 1, 0); PG8_STAGE(PG8_SA(0, 1), a2 + hstepA, voffA);
;             PG8_WAIT_V(8); PG8_WAIT_L(0); PG8_BAR; PG8_MMA(0, 0, At, B0); PG8_MMA(0, 1, At, B1); PG8_BAR; PG8_SCHED;
	v_mfma_f32_16x16x32_bf16 v[94:97], v[98:101], v[200:203], v[94:97]
	v_mfma_f32_16x16x32_bf16 v[90:93], v[150:153], v[200:203], v[90:93]
	v_mfma_f32_16x16x32_bf16 v[86:89], v[98:101], v[208:211], v[86:89]
	v_mfma_f32_16x16x32_bf16 v[82:85], v[150:153], v[208:211], v[82:85]
	v_mfma_f32_16x16x32_bf16 v[78:81], v[98:101], v[216:219], v[78:81]
	v_mfma_f32_16x16x32_bf16 v[74:77], v[150:153], v[216:219], v[74:77]
	v_mfma_f32_16x16x32_bf16 v[70:73], v[98:101], v[224:227], v[70:73]
	v_mfma_f32_16x16x32_bf16 v[66:69], v[150:153], v[224:227], v[66:69]
	v_mfma_f32_16x16x32_bf16 v[94:97], v[102:105], v[204:207], v[94:97]
	v_mfma_f32_16x16x32_bf16 v[90:93], v[180:183], v[204:207], v[90:93]
	v_mfma_f32_16x16x32_bf16 v[86:89], v[102:105], v[212:215], v[86:89]
	v_mfma_f32_16x16x32_bf16 v[82:85], v[180:183], v[212:215], v[82:85]
	v_mfma_f32_16x16x32_bf16 v[78:81], v[102:105], v[220:223], v[78:81]
	v_mfma_f32_16x16x32_bf16 v[74:77], v[180:183], v[220:223], v[74:77]
	v_mfma_f32_16x16x32_bf16 v[70:73], v[102:105], v[228:231], v[70:73]
	v_mfma_f32_16x16x32_bf16 v[66:69], v[180:183], v[228:231], v[66:69]
	v_mfma_f32_16x16x32_bf16 v[30:33], v[184:187], v[200:203], v[30:33]
	v_mfma_f32_16x16x32_bf16 v[26:29], v[192:195], v[200:203], v[26:29]
	v_mfma_f32_16x16x32_bf16 v[22:25], v[184:187], v[208:211], v[22:25]
	v_mfma_f32_16x16x32_bf16 v[18:21], v[192:195], v[208:211], v[18:21]
	v_mfma_f32_16x16x32_bf16 v[14:17], v[184:187], v[216:219], v[14:17]
	v_mfma_f32_16x16x32_bf16 v[10:13], v[192:195], v[216:219], v[10:13]
	v_mfma_f32_16x16x32_bf16 v[6:9], v[184:187], v[224:227], v[6:9]
	v_mfma_f32_16x16x32_bf16 v[2:5], v[192:195], v[224:227], v[2:5]
	v_mfma_f32_16x16x32_bf16 v[30:33], v[188:191], v[204:207], v[30:33]
	v_mfma_f32_16x16x32_bf16 v[26:29], v[196:199], v[204:207], v[26:29]
	v_mfma_f32_16x16x32_bf16 v[22:25], v[188:191], v[212:215], v[22:25]
	v_mfma_f32_16x16x32_bf16 v[18:21], v[196:199], v[212:215], v[18:21]
	v_mfma_f32_16x16x32_bf16 v[14:17], v[188:191], v[220:223], v[14:17]
	v_mfma_f32_16x16x32_bf16 v[10:13], v[196:199], v[220:223], v[10:13]
	v_mfma_f32_16x16x32_bf16 v[6:9], v[188:191], v[228:231], v[6:9]
	v_mfma_f32_16x16x32_bf16 v[2:5], v[196:199], v[228:231], v[2:5]
	s_barrier
	s_setprio 0
	s_add_i32 s45, 0, 0x18000
	s_add_i32 s6, 0, 0x1c000
	v_add_u32_e32 v180, s45, v167
	v_add_u32_e32 v196, s6, v167
	ds_read_b128 v[98:101], v180
	ds_read_b128 v[102:105], v180 offset:1024
	ds_read_b128 v[150:153], v180 offset:2048
	ds_read_b128 v[180:183], v180 offset:3072
	ds_read_b128 v[184:187], v196
	ds_read_b128 v[188:191], v196 offset:1024
	ds_read_b128 v[192:195], v196 offset:2048
	ds_read_b128 v[196:199], v196 offset:3072
	s_add_u32 s10, s28, 0x40000
	s_addc_u32 s11, s29, 0
	s_mov_b32 m0, s49
	v_lshl_add_u64 v[248:249], s[10:11], 0, v[144:145]
	ds_read_b128 v[200:203], v179 offset:32768
	ds_read_b128 v[204:207], v179 offset:33792
	ds_read_b128 v[208:211], v179 offset:34816
	ds_read_b128 v[212:215], v179 offset:35840
	ds_read_b128 v[216:219], v179 offset:36864
	ds_read_b128 v[220:223], v179 offset:37888
	ds_read_b128 v[224:227], v179 offset:38912
	ds_read_b128 v[228:231], v179 offset:39936
	global_load_lds_dwordx4 v[248:249], off
	v_lshl_add_u64 v[248:249], s[10:11], 0, v[140:141]
	s_mov_b32 m0, s62
	s_nop 0
	global_load_lds_dwordx4 v[248:249], off
	s_waitcnt vmcnt(8)
	s_waitcnt lgkmcnt(0)
	s_setprio 1
	s_barrier
	v_mfma_f32_16x16x32_bf16 v[134:137], v[98:101], v[200:203], v[134:137]
	v_mfma_f32_16x16x32_bf16 v[130:133], v[150:153], v[200:203], v[130:133]
	v_mfma_f32_16x16x32_bf16 v[126:129], v[98:101], v[208:211], v[126:129]
	v_mfma_f32_16x16x32_bf16 v[122:125], v[150:153], v[208:211], v[122:125]
	v_mfma_f32_16x16x32_bf16 v[118:121], v[98:101], v[216:219], v[118:121]
	v_mfma_f32_16x16x32_bf16 v[114:117], v[150:153], v[216:219], v[114:117]
	v_mfma_f32_16x16x32_bf16 v[110:113], v[98:101], v[224:227], v[110:113]
	v_mfma_f32_16x16x32_bf16 v[106:109], v[150:153], v[224:227], v[106:109]
	v_mfma_f32_16x16x32_bf16 v[134:137], v[102:105], v[204:207], v[134:137]
	v_mfma_f32_16x16x32_bf16 v[130:133], v[180:183], v[204:207], v[130:133]
	v_mfma_f32_16x16x32_bf16 v[126:129], v[102:105], v[212:215], v[126:129]
	v_mfma_f32_16x16x32_bf16 v[122:125], v[180:183], v[212:215], v[122:125]
	v_mfma_f32_16x16x32_bf16 v[118:121], v[102:105], v[220:223], v[118:121]
	v_mfma_f32_16x16x32_bf16 v[114:117], v[180:183], v[220:223], v[114:117]
	v_mfma_f32_16x16x32_bf16 v[110:113], v[102:105], v[228:231], v[110:113]
	v_mfma_f32_16x16x32_bf16 v[106:109], v[180:183], v[228:231], v[106:109]
	v_mfma_f32_16x16x32_bf16 v[62:65], v[184:187], v[200:203], v[62:65]
	v_mfma_f32_16x16x32_bf16 v[58:61], v[192:195], v[200:203], v[58:61]
	v_mfma_f32_16x16x32_bf16 v[54:57], v[184:187], v[208:211], v[54:57]
	v_mfma_f32_16x16x32_bf16 v[50:53], v[192:195], v[208:211], v[50:53]
	v_mfma_f32_16x16x32_bf16 v[46:49], v[184:187], v[216:219], v[46:49]
	v_mfma_f32_16x16x32_bf16 v[42:45], v[192:195], v[216:219], v[42:45]
	v_mfma_f32_16x16x32_bf16 v[38:41], v[184:187], v[224:227], v[38:41]
	v_mfma_f32_16x16x32_bf16 v[34:37], v[192:195], v[224:227], v[34:37]
	v_mfma_f32_16x16x32_bf16 v[62:65], v[188:191], v[204:207], v[62:65]
	v_mfma_f32_16x16x32_bf16 v[58:61], v[196:199], v[204:207], v[58:61]
	v_mfma_f32_16x16x32_bf16 v[54:57], v[188:191], v[212:215], v[54:57]
	v_mfma_f32_16x16x32_bf16 v[50:53], v[196:199], v[212:215], v[50:53]
	v_mfma_f32_16x16x32_bf16 v[46:49], v[188:191], v[220:223], v[46:49]
	v_mfma_f32_16x16x32_bf16 v[42:45], v[196:199], v[220:223], v[42:45]
	v_mfma_f32_16x16x32_bf16 v[38:41], v[188:191], v[228:231], v[38:41]
	v_mfma_f32_16x16x32_bf16 v[34:37], v[196:199], v[228:231], v[34:37]
	s_barrier
; #define PG8_STAGE(bufoff, gbase, voff) do { _Pragma("unroll") for (int _i = 0; _i < 2; ++_i) \
;         __builtin_amdgcn_global_load_lds((const unsigned*)((const char*)(gbase) + (voff)[_i]), (LAS unsigned*)(lds + (bufoff) + ldsw + _i * 8192), 16, 0, 0); } while (0)
; #define PG8_LDA(dst, b, h) do { _Pragma("unroll") for (int m = 0; m < 4; ++m) _Pragma("unroll") for (int k = 0; k < 2; ++k) dst[m][k] = *(const LAS bf16x8*)(lds + PG8_SA(b, h) + aoff + m * 2048 + k * 1024); } while (0)
; #define PG8_MMA(ai, bj, At, Bt) do { __builtin_amdgcn_s_setprio(1); _Pragma("unroll") for (int m = 0; m < 4; ++m) _Pragma("unroll") for (int n = 0; n < 2; ++n) _Pragma("unroll") for (int k = 0; k < 2; ++k) \
;         acc[ai][bj][m][n] = __builtin_amdgcn_mfma_f32_16x16x32_bf16(Bt[n][k], At[m][k], acc[ai][bj][m][n], 0, 0, 0); __builtin_amdgcn_s_setprio(0); } while (0)
; #define PG8_WAIT_V(n) asm volatile("s_waitcnt vmcnt(" #n ")" ::: "memory")
; #define PG8_WAIT_L(n) asm volatile("s_waitcnt lgkmcnt(" #n ")" ::: "memory")
; #define PG8_BAR __builtin_amdgcn_s_barrier()
; #define PG8_SCHED __builtin_amdgcn_sched_barrier(0)
; template <class Epi, class Sched>
; __device__ __forceinline__ void gemm_phase(LAS unsigned char* lds, const Gemm g, const Sched S, const Epi E, const int tid) {
;     ...
;             PG8_LDA(At, 1, 1); PG8_STAGE(PG8_SB(1, 0), b3, voffB); PG8_STAGE(PG8_SB(1, 1), b3 + hstepB, voffB); PG8_STAGE(PG8_SA(1, 0), a3, voffA);
;             PG8_WAIT_V(8); PG8_WAIT_L(0); PG8_BAR; PG8_MMA(1, 0, At, B0); PG8_MMA(1, 1, At, B1); PG8_BAR; PG8_SCHED;
;         }
	s_setprio 0
	s_add_i32 s7, s45, s46
	v_lshl_add_u64 v[154:155], v[154:155], 0, s[64:65]
	s_mov_b32 m0, s7
	ds_read_b128 v[200:203], v179 offset:49152
	ds_read_b128 v[204:207], v179 offset:50176
	ds_read_b128 v[208:211], v179 offset:51200
	ds_read_b128 v[212:215], v179 offset:52224
	ds_read_b128 v[216:219], v179 offset:53248
	ds_read_b128 v[220:223], v179 offset:54272
	ds_read_b128 v[224:227], v179 offset:55296
	ds_read_b128 v[228:231], v179 offset:56320
	global_load_lds_dwordx4 v[154:155], off
	s_add_i32 m0, s7, 0x2000
	s_add_u32 s10, s26, 0x80080
	v_lshl_add_u64 v[154:155], v[232:233], 0, s[64:65]
	s_addc_u32 s11, s27, 0
	s_add_i32 s6, s6, s46
	global_load_lds_dwordx4 v[154:155], off
	v_lshl_add_u64 v[154:155], s[10:11], 0, v[142:143]
	s_mov_b32 m0, s6
	s_nop 0
	global_load_lds_dwordx4 v[154:155], off
	v_lshl_add_u64 v[154:155], s[10:11], 0, v[138:139]
	s_add_i32 m0, s6, 0x2000
	s_nop 0
	global_load_lds_dwordx4 v[154:155], off
	v_lshl_add_u64 v[154:155], v[234:235], 0, s[64:65]
	s_mov_b32 m0, s84
	s_nop 0
	global_load_lds_dwordx4 v[154:155], off
	v_lshl_add_u64 v[154:155], v[246:247], 0, s[64:65]
	s_mov_b32 m0, s85
	s_nop 0
	global_load_lds_dwordx4 v[154:155], off
	s_waitcnt vmcnt(8)
	s_waitcnt lgkmcnt(0)
	s_setprio 1
	s_barrier
	v_mfma_f32_16x16x32_bf16 v[94:97], v[98:101], v[200:203], v[94:97]
	v_mfma_f32_16x16x32_bf16 v[90:93], v[150:153], v[200:203], v[90:93]
	v_mfma_f32_16x16x32_bf16 v[86:89], v[98:101], v[208:211], v[86:89]
	v_mfma_f32_16x16x32_bf16 v[82:85], v[150:153], v[208:211], v[82:85]
	v_mfma_f32_16x16x32_bf16 v[78:81], v[98:101], v[216:219], v[78:81]
	v_mfma_f32_16x16x32_bf16 v[74:77], v[150:153], v[216:219], v[74:77]
	v_mfma_f32_16x16x32_bf16 v[70:73], v[98:101], v[224:227], v[70:73]
	v_mfma_f32_16x16x32_bf16 v[66:69], v[150:153], v[224:227], v[66:69]
	v_mfma_f32_16x16x32_bf16 v[94:97], v[102:105], v[204:207], v[94:97]
	v_mfma_f32_16x16x32_bf16 v[90:93], v[180:183], v[204:207], v[90:93]
	v_mfma_f32_16x16x32_bf16 v[86:89], v[102:105], v[212:215], v[86:89]
	v_mfma_f32_16x16x32_bf16 v[82:85], v[180:183], v[212:215], v[82:85]
	v_mfma_f32_16x16x32_bf16 v[78:81], v[102:105], v[220:223], v[78:81]
	v_mfma_f32_16x16x32_bf16 v[74:77], v[180:183], v[220:223], v[74:77]
	v_mfma_f32_16x16x32_bf16 v[70:73], v[102:105], v[228:231], v[70:73]
	v_mfma_f32_16x16x32_bf16 v[66:69], v[180:183], v[228:231], v[66:69]
	v_mfma_f32_16x16x32_bf16 v[30:33], v[184:187], v[200:203], v[30:33]
	v_mfma_f32_16x16x32_bf16 v[26:29], v[192:195], v[200:203], v[26:29]
	v_mfma_f32_16x16x32_bf16 v[22:25], v[184:187], v[208:211], v[22:25]
	v_mfma_f32_16x16x32_bf16 v[18:21], v[192:195], v[208:211], v[18:21]
	v_mfma_f32_16x16x32_bf16 v[14:17], v[184:187], v[216:219], v[14:17]
	v_mfma_f32_16x16x32_bf16 v[10:13], v[192:195], v[216:219], v[10:13]
	v_mfma_f32_16x16x32_bf16 v[6:9], v[184:187], v[224:227], v[6:9]
	v_mfma_f32_16x16x32_bf16 v[2:5], v[192:195], v[224:227], v[2:5]
	v_mfma_f32_16x16x32_bf16 v[30:33], v[188:191], v[204:207], v[30:33]
	v_mfma_f32_16x16x32_bf16 v[26:29], v[196:199], v[204:207], v[26:29]
	v_mfma_f32_16x16x32_bf16 v[22:25], v[188:191], v[212:215], v[22:25]
	v_mfma_f32_16x16x32_bf16 v[18:21], v[196:199], v[212:215], v[18:21]
	v_mfma_f32_16x16x32_bf16 v[14:17], v[188:191], v[220:223], v[14:17]
	v_mfma_f32_16x16x32_bf16 v[10:13], v[196:199], v[220:223], v[10:13]
	v_mfma_f32_16x16x32_bf16 v[6:9], v[188:191], v[228:231], v[6:9]
	v_mfma_f32_16x16x32_bf16 v[2:5], v[196:199], v[228:231], v[2:5]
	s_barrier
	s_setprio 0
	s_add_i32 vcc_hi, vcc_hi, 2
	s_add_u32 s97, s97, 0x100
	s_addc_u32 vcc_lo, vcc_lo, 0
	s_add_u32 s22, s22, 0x100
	s_addc_u32 s23, s23, 0
	s_cmp_gt_u32 vcc_hi, 29
	s_cbranch_scc0 .LBB0_299
	s_and_b64 vcc, exec, s[18:19]
	s_cbranch_vccz .LBB0_302
	s_barrier

;     __host__ __device__ bool next(int i, Unit& u) const { const int L = i * G + c; if (L >= 32) return false; u.pm = L; u.pn = L >> 4; return true; }
; #define PG8_STAGE(bufoff, gbase, voff) do { _Pragma("unroll") for (int _i = 0; _i < 2; ++_i) \
;         __builtin_amdgcn_global_load_lds((const unsigned*)((const char*)(gbase) + (voff)[_i]), (LAS unsigned*)(lds + (bufoff) + ldsw + _i * 8192), 16, 0, 0); } while (0)
; #define PG8_LDA(dst, b, h) do { _Pragma("unroll") for (int m = 0; m < 4; ++m) _Pragma("unroll") for (int k = 0; k < 2; ++k) dst[m][k] = *(const LAS bf16x8*)(lds + PG8_SA(b, h) + aoff + m * 2048 + k * 1024); } while (0)
; #define PG8_LDB(dst, b, h) do { _Pragma("unroll") for (int n = 0; n < 2; ++n) _Pragma("unroll") for (int k = 0; k < 2; ++k) dst[n][k] = *(const LAS bf16x8*)(lds + PG8_SB(b, h) + boff + n * 2048 + k * 1024); } while (0)
; template <class Epi, class Sched>
; __device__ __forceinline__ void gemm_phase(LAS unsigned char* lds, const Gemm g, const Sched S, const Epi E, const int tid) {
;     ...
;         const bool has_next = S.next(ui + 1, nxt);
;         const char* nA = has_next ? (const char*)g.A + (size_t)nxt.pm * tstepA : cA; const char* nB = has_next ? (const char*)g.Bt + (size_t)nxt.pn * tstepB : cB;
;         for (int t = 0; t < nt; t += 2) {
;             const bool last = (t == nt - 2);
;             const char* a1 = cA + (size_t)(t + 1) * kstep;
;             const char* a2 = last ? nA : cA + (size_t)(t + 2) * kstep; const char* b2 = last ? nB : cB + (size_t)(t + 2) * kstep;
;             const char* a3 = a2 + kstep; const char* b3 = b2 + kstep;
;             PG8_LDB(B0, 0, 0); PG8_LDB(B1, 0, 1); PG8_SCHED; PG8_LDA(At, 0, 0); PG8_STAGE(PG8_SA(1, 1), a1 + hstepA, voffA);
;             PG8_WAIT_V(8); PG8_WAIT_L(0); PG8_BAR; PG8_MMA(0, 0, At, B0); PG8_MMA(0, 1, At, B1); PG8_BAR; PG8_SCHED;
;             PG8_LDA(At, 0, 1); PG8_STAGE(PG8_SB(0, 0), b2, voffB); PG8_STAGE(PG8_SB(0, 1), b2 + hstepB, voffB); PG8_STAGE(PG8_SA(0, 0), a2, voffA);
;             PG8_WAIT_V(8); PG8_WAIT_L(0); PG8_BAR; PG8_MMA(1, 0, At, B0); PG8_MMA(1, 1, At, B1); PG8_BAR; PG8_SCHED;
;             PG8_LDB(B0, 1, 0); PG8_LDB(B1, 1, 1); PG8_SCHED; PG8_LDA(At, 1, 0); PG8_STAGE(PG8_SA(0, 1), a2 + hstepA, voffA);
;             PG8_WAIT_V(8); PG8_WAIT_L(0); PG8_BAR; PG8_MMA(0, 0, At, B0); PG8_MMA(0, 1, At, B1); PG8_BAR; PG8_SCHED;
.LBB0_310:
	s_mov_b32 s6, s92
	s_ashr_i32 s92, s89, 4
	s_cmp_lt_i32 s89, 32
	s_mov_b64 s[42:43], s[4:5]
	s_cselect_b64 s[4:5], -1, 0
	s_and_b64 s[4:5], s[4:5], exec
	s_cselect_b32 s4, s92, s6
	s_ashr_i32 s5, s4, 31
	s_lshl_b64 s[4:5], s[4:5], 17
	s_add_u32 s4, s25, s4
	s_addc_u32 s5, s46, s5
	s_cmp_lt_i32 s89, 32
	s_cselect_b64 s[10:11], -1, 0
	s_and_b64 s[10:11], s[10:11], exec
	s_cselect_b32 s10, s89, s93
	v_add_u32_e32 v130, s44, v70
	s_cselect_b32 s26, s4, s42
	s_cselect_b32 s27, s5, s43
	s_ashr_i32 s11, s10, 31
	ds_read_b128 v[2:5], v130
	ds_read_b128 v[6:9], v130 offset:1024
	ds_read_b128 v[10:13], v130 offset:2048
	ds_read_b128 v[14:17], v130 offset:3072
	s_lshl_b64 s[10:11], s[10:11], 17
	s_mov_b64 s[40:41], s[16:17]
	s_add_u32 s16, s8, s10
	s_addc_u32 s17, s9, s11
	s_cmp_lt_i32 s89, 32
	s_cselect_b64 s[22:23], -1, 0
	s_and_b64 s[10:11], s[22:23], exec
	s_cselect_b32 s29, s17, s41
	s_cselect_b32 s28, s16, s40
	s_add_u32 s10, s40, 0x10080
	s_addc_u32 s11, s41, 0
	s_add_i32 s97, s37, 0xc000
	v_lshl_add_u64 v[50:51], s[10:11], 0, v[68:69]
	s_mov_b32 m0, s97
	s_add_i32 s13, s37, 0xe000
	ds_read_b128 v[18:21], v71
	ds_read_b128 v[22:25], v71 offset:1024
	ds_read_b128 v[26:29], v71 offset:2048
	ds_read_b128 v[30:33], v71 offset:3072
	ds_read_b128 v[34:37], v71 offset:4096
	ds_read_b128 v[38:41], v71 offset:5120
	ds_read_b128 v[42:45], v71 offset:6144
	ds_read_b128 v[46:49], v71 offset:7168
	global_load_lds_dwordx4 v[50:51], off
	v_lshl_add_u64 v[50:51], s[10:11], 0, v[66:67]
	s_mov_b32 m0, s13
	s_nop 0
	global_load_lds_dwordx4 v[50:51], off
	s_waitcnt vmcnt(8)
	s_waitcnt lgkmcnt(0)
	s_setprio 1
	s_barrier
	v_mfma_f32_16x16x32_bf16 v[50:53], v[2:5], v[18:21], 0
	v_mfma_f32_16x16x32_bf16 v[18:21], v[10:13], v[18:21], 0
	v_mfma_f32_16x16x32_bf16 v[50:53], v[6:9], v[22:25], v[50:53]
	v_mfma_f32_16x16x32_bf16 v[18:21], v[14:17], v[22:25], v[18:21]
	v_mfma_f32_16x16x32_bf16 v[22:25], v[2:5], v[26:29], 0
	v_mfma_f32_16x16x32_bf16 v[26:29], v[10:13], v[26:29], 0
	v_mfma_f32_16x16x32_bf16 v[22:25], v[6:9], v[30:33], v[22:25]
	v_mfma_f32_16x16x32_bf16 v[26:29], v[14:17], v[30:33], v[26:29]
	v_mfma_f32_16x16x32_bf16 v[30:33], v[2:5], v[34:37], 0
	v_mfma_f32_16x16x32_bf16 v[34:37], v[10:13], v[34:37], 0
	v_mfma_f32_16x16x32_bf16 v[30:33], v[6:9], v[38:41], v[30:33]
	v_mfma_f32_16x16x32_bf16 v[34:37], v[14:17], v[38:41], v[34:37]
	v_mfma_f32_16x16x32_bf16 v[38:41], v[2:5], v[42:45], 0
	v_mfma_f32_16x16x32_bf16 v[42:45], v[10:13], v[42:45], 0
	v_mfma_f32_16x16x32_bf16 v[38:41], v[6:9], v[46:49], v[38:41]
	v_mfma_f32_16x16x32_bf16 v[42:45], v[14:17], v[46:49], v[42:45]
	s_barrier
	s_setprio 0
	s_add_i32 s96, s44, s47
	v_lshl_add_u64 v[120:121], s[42:43], 0, v[68:69]
	s_mov_b64 s[6:7], 0x100
	s_add_i32 s94, s96, 0x2000
	v_lshl_add_u64 v[88:89], v[120:121], 0, s[6:7]
	s_mov_b32 m0, s96
	v_lshl_add_u64 v[122:123], s[42:43], 0, v[66:67]
	s_add_u32 s10, s42, 0x10100
	ds_read_b128 v[46:49], v71 offset:16384
	ds_read_b128 v[54:57], v71 offset:17408
	ds_read_b128 v[58:61], v71 offset:18432
	ds_read_b128 v[62:65], v71 offset:19456
	ds_read_b128 v[72:75], v71 offset:20480
	ds_read_b128 v[76:79], v71 offset:21504
	ds_read_b128 v[80:83], v71 offset:22528
	ds_read_b128 v[84:87], v71 offset:23552
	global_load_lds_dwordx4 v[88:89], off
	v_lshl_add_u64 v[88:89], v[122:123], 0, s[6:7]
	s_mov_b32 m0, s94
	s_addc_u32 s11, s43, 0
	global_load_lds_dwordx4 v[88:89], off
	v_lshl_add_u64 v[88:89], s[10:11], 0, v[68:69]
	s_mov_b32 m0, s48
	v_lshl_add_u64 v[124:125], s[40:41], 0, v[68:69]
	global_load_lds_dwordx4 v[88:89], off
	v_lshl_add_u64 v[88:89], s[10:11], 0, v[66:67]
	s_mov_b32 m0, s49
	v_lshl_add_u64 v[126:127], s[40:41], 0, v[66:67]
	global_load_lds_dwordx4 v[88:89], off
	v_lshl_add_u64 v[88:89], v[124:125], 0, s[6:7]
	s_mov_b32 m0, s37
	s_nop 0
	global_load_lds_dwordx4 v[88:89], off
	v_lshl_add_u64 v[88:89], v[126:127], 0, s[6:7]
	s_mov_b32 m0, s62
	s_nop 0
	global_load_lds_dwordx4 v[88:89], off
	s_waitcnt vmcnt(8)
	s_waitcnt lgkmcnt(0)
	s_setprio 1
	s_barrier
	v_mfma_f32_16x16x32_bf16 v[88:91], v[2:5], v[46:49], 0
	v_mfma_f32_16x16x32_bf16 v[46:49], v[10:13], v[46:49], 0
	v_mfma_f32_16x16x32_bf16 v[88:91], v[6:9], v[54:57], v[88:91]
	v_mfma_f32_16x16x32_bf16 v[46:49], v[14:17], v[54:57], v[46:49]
	v_mfma_f32_16x16x32_bf16 v[54:57], v[2:5], v[58:61], 0
	v_mfma_f32_16x16x32_bf16 v[58:61], v[10:13], v[58:61], 0
	v_mfma_f32_16x16x32_bf16 v[54:57], v[6:9], v[62:65], v[54:57]
	v_mfma_f32_16x16x32_bf16 v[58:61], v[14:17], v[62:65], v[58:61]
	v_mfma_f32_16x16x32_bf16 v[62:65], v[2:5], v[72:75], 0
	v_mfma_f32_16x16x32_bf16 v[2:5], v[2:5], v[80:83], 0
	v_mfma_f32_16x16x32_bf16 v[62:65], v[6:9], v[76:79], v[62:65]
	v_mfma_f32_16x16x32_bf16 v[2:5], v[6:9], v[84:87], v[2:5]
	v_mfma_f32_16x16x32_bf16 v[6:9], v[10:13], v[80:83], 0
	v_mfma_f32_16x16x32_bf16 v[72:75], v[10:13], v[72:75], 0
	v_mfma_f32_16x16x32_bf16 v[6:9], v[14:17], v[84:87], v[6:9]
	v_mfma_f32_16x16x32_bf16 v[72:75], v[14:17], v[76:79], v[72:75]
	s_barrier
	s_setprio 0
	v_add_u32_e32 v131, s45, v70
	ds_read_b128 v[10:13], v131
	ds_read_b128 v[14:17], v131 offset:1024
	ds_read_b128 v[76:79], v131 offset:2048
	ds_read_b128 v[80:83], v131 offset:3072
	s_add_u32 s10, s40, 0x10100
	s_addc_u32 s11, s41, 0
	s_mov_b32 m0, s68
	v_lshl_add_u64 v[128:129], s[10:11], 0, v[68:69]
	ds_read_b128 v[84:87], v71 offset:32768
	ds_read_b128 v[92:95], v71 offset:33792
	ds_read_b128 v[96:99], v71 offset:34816
	ds_read_b128 v[100:103], v71 offset:35840
	ds_read_b128 v[104:107], v71 offset:36864
	ds_read_b128 v[108:111], v71 offset:37888
	ds_read_b128 v[112:115], v71 offset:38912
	ds_read_b128 v[116:119], v71 offset:39936
	global_load_lds_dwordx4 v[128:129], off
	v_lshl_add_u64 v[128:129], s[10:11], 0, v[66:67]
	s_mov_b32 m0, s69
	s_nop 0
	global_load_lds_dwordx4 v[128:129], off
	s_waitcnt vmcnt(8)
	s_waitcnt lgkmcnt(0)
	s_setprio 1
	s_barrier
; #define PG8_STAGE(bufoff, gbase, voff) do { _Pragma("unroll") for (int _i = 0; _i < 2; ++_i) \
;         __builtin_amdgcn_global_load_lds((const unsigned*)((const char*)(gbase) + (voff)[_i]), (LAS unsigned*)(lds + (bufoff) + ldsw + _i * 8192), 16, 0, 0); } while (0)
; #define PG8_LDA(dst, b, h) do { _Pragma("unroll") for (int m = 0; m < 4; ++m) _Pragma("unroll") for (int k = 0; k < 2; ++k) dst[m][k] = *(const LAS bf16x8*)(lds + PG8_SA(b, h) + aoff + m * 2048 + k * 1024); } while (0)
; #define PG8_LDB(dst, b, h) do { _Pragma("unroll") for (int n = 0; n < 2; ++n) _Pragma("unroll") for (int k = 0; k < 2; ++k) dst[n][k] = *(const LAS bf16x8*)(lds + PG8_SB(b, h) + boff + n * 2048 + k * 1024); } while (0)
; #define PG8_MMA(ai, bj, At, Bt) do { __builtin_amdgcn_s_setprio(1); _Pragma("unroll") for (int m = 0; m < 4; ++m) _Pragma("unroll") for (int n = 0; n < 2; ++n) _Pragma("unroll") for (int k = 0; k < 2; ++k) \
;         acc[ai][bj][m][n] = __builtin_amdgcn_mfma_f32_16x16x32_bf16(Bt[n][k], At[m][k], acc[ai][bj][m][n], 0, 0, 0); __builtin_amdgcn_s_setprio(0); } while (0)
; #define PG8_WAIT_V(n) asm volatile("s_waitcnt vmcnt(" #n ")" ::: "memory")
; template <class Epi, class Sched>
; __device__ __forceinline__ void gemm_phase(LAS unsigned char* lds, const Gemm g, const Sched S, const Epi E, const int tid) {
;     ...
;             PG8_LDB(B0, 0, 0); PG8_LDB(B1, 0, 1); PG8_SCHED; PG8_LDA(At, 0, 0); PG8_STAGE(PG8_SA(1, 1), a1 + hstepA, voffA);
;             PG8_WAIT_V(8); PG8_WAIT_L(0); PG8_BAR; PG8_MMA(0, 0, At, B0); PG8_MMA(0, 1, At, B1); PG8_BAR; PG8_SCHED;
;             PG8_LDA(At, 0, 1); PG8_STAGE(PG8_SB(0, 0), b2, voffB); PG8_STAGE(PG8_SB(0, 1), b2 + hstepB, voffB); PG8_STAGE(PG8_SA(0, 0), a2, voffA);
;             PG8_WAIT_V(8); PG8_WAIT_L(0); PG8_BAR; PG8_MMA(1, 0, At, B0); PG8_MMA(1, 1, At, B1); PG8_BAR; PG8_SCHED;
;             PG8_LDB(B0, 1, 0); PG8_LDB(B1, 1, 1); PG8_SCHED; PG8_LDA(At, 1, 0); PG8_STAGE(PG8_SA(0, 1), a2 + hstepA, voffA);
;             PG8_WAIT_V(8); PG8_WAIT_L(0); PG8_BAR; PG8_MMA(0, 0, At, B0); PG8_MMA(0, 1, At, B1); PG8_BAR; PG8_SCHED;
;             PG8_LDA(At, 1, 1); PG8_STAGE(PG8_SB(1, 0), b3, voffB); PG8_STAGE(PG8_SB(1, 1), b3 + hstepB, voffB); PG8_STAGE(PG8_SA(1, 0), a3, voffA);
;             PG8_WAIT_V(8); PG8_WAIT_L(0); PG8_BAR; PG8_MMA(1, 0, At, B0); PG8_MMA(1, 1, At, B1); PG8_BAR; PG8_SCHED;
	v_mfma_f32_16x16x32_bf16 v[50:53], v[10:13], v[84:87], v[50:53]
	v_mfma_f32_16x16x32_bf16 v[18:21], v[76:79], v[84:87], v[18:21]
	v_mfma_f32_16x16x32_bf16 v[22:25], v[10:13], v[96:99], v[22:25]
	v_mfma_f32_16x16x32_bf16 v[26:29], v[76:79], v[96:99], v[26:29]
	v_mfma_f32_16x16x32_bf16 v[30:33], v[10:13], v[104:107], v[30:33]
	v_mfma_f32_16x16x32_bf16 v[34:37], v[76:79], v[104:107], v[34:37]
	v_mfma_f32_16x16x32_bf16 v[38:41], v[10:13], v[112:115], v[38:41]
	v_mfma_f32_16x16x32_bf16 v[42:45], v[76:79], v[112:115], v[42:45]
	v_mfma_f32_16x16x32_bf16 v[50:53], v[14:17], v[92:95], v[50:53]
	v_mfma_f32_16x16x32_bf16 v[18:21], v[80:83], v[92:95], v[18:21]
	v_mfma_f32_16x16x32_bf16 v[22:25], v[14:17], v[100:103], v[22:25]
	v_mfma_f32_16x16x32_bf16 v[26:29], v[80:83], v[100:103], v[26:29]
	v_mfma_f32_16x16x32_bf16 v[30:33], v[14:17], v[108:111], v[30:33]
	v_mfma_f32_16x16x32_bf16 v[34:37], v[80:83], v[108:111], v[34:37]
	v_mfma_f32_16x16x32_bf16 v[38:41], v[14:17], v[116:119], v[38:41]
	v_mfma_f32_16x16x32_bf16 v[42:45], v[80:83], v[116:119], v[42:45]
	s_barrier
	s_setprio 0
	s_add_i32 vcc_lo, s45, s47
	s_mov_b64 s[6:7], 0x180
	s_add_i32 s95, vcc_lo, 0x2000
	v_lshl_add_u64 v[120:121], v[120:121], 0, s[6:7]
	s_mov_b32 m0, vcc_lo
	s_add_u32 s10, s42, 0x10180
	ds_read_b128 v[84:87], v71 offset:49152
	ds_read_b128 v[92:95], v71 offset:50176
	ds_read_b128 v[96:99], v71 offset:51200
	ds_read_b128 v[100:103], v71 offset:52224
	ds_read_b128 v[104:107], v71 offset:53248
	ds_read_b128 v[108:111], v71 offset:54272
	ds_read_b128 v[112:115], v71 offset:55296
	ds_read_b128 v[116:119], v71 offset:56320
	global_load_lds_dwordx4 v[120:121], off
	v_lshl_add_u64 v[120:121], v[122:123], 0, s[6:7]
	s_mov_b32 m0, s95
	s_addc_u32 s11, s43, 0
	global_load_lds_dwordx4 v[120:121], off
	v_lshl_add_u64 v[120:121], s[10:11], 0, v[68:69]
	s_mov_b32 m0, s85
	s_nop 0
	global_load_lds_dwordx4 v[120:121], off
	v_lshl_add_u64 v[120:121], s[10:11], 0, v[66:67]
	s_mov_b32 m0, s88
	s_nop 0
	global_load_lds_dwordx4 v[120:121], off
	v_lshl_add_u64 v[120:121], v[124:125], 0, s[6:7]
	s_mov_b32 m0, s83
	s_nop 0
	global_load_lds_dwordx4 v[120:121], off
	v_lshl_add_u64 v[120:121], v[126:127], 0, s[6:7]
	s_mov_b32 m0, s84
	s_nop 0
	global_load_lds_dwordx4 v[120:121], off
	s_waitcnt vmcnt(8)
	s_waitcnt lgkmcnt(0)
	s_setprio 1
	s_barrier
	v_mfma_f32_16x16x32_bf16 v[46:49], v[76:79], v[84:87], v[46:49]
	v_mfma_f32_16x16x32_bf16 v[54:57], v[10:13], v[96:99], v[54:57]
	v_mfma_f32_16x16x32_bf16 v[58:61], v[76:79], v[96:99], v[58:61]
	v_mfma_f32_16x16x32_bf16 v[62:65], v[10:13], v[104:107], v[62:65]
	v_mfma_f32_16x16x32_bf16 v[2:5], v[10:13], v[112:115], v[2:5]
	v_mfma_f32_16x16x32_bf16 v[6:9], v[76:79], v[112:115], v[6:9]
	v_mfma_f32_16x16x32_bf16 v[88:91], v[10:13], v[84:87], v[88:91]
	v_mfma_f32_16x16x32_bf16 v[46:49], v[80:83], v[92:95], v[46:49]
	v_mfma_f32_16x16x32_bf16 v[54:57], v[14:17], v[100:103], v[54:57]
	v_mfma_f32_16x16x32_bf16 v[58:61], v[80:83], v[100:103], v[58:61]
	v_mfma_f32_16x16x32_bf16 v[62:65], v[14:17], v[108:111], v[62:65]
	v_mfma_f32_16x16x32_bf16 v[72:75], v[76:79], v[104:107], v[72:75]
	v_mfma_f32_16x16x32_bf16 v[2:5], v[14:17], v[116:119], v[2:5]
	v_mfma_f32_16x16x32_bf16 v[6:9], v[80:83], v[116:119], v[6:9]
	v_mfma_f32_16x16x32_bf16 v[88:91], v[14:17], v[92:95], v[88:91]
	v_mfma_f32_16x16x32_bf16 v[72:75], v[80:83], v[108:111], v[72:75]
	s_barrier
	s_setprio 0
	ds_read_b128 v[10:13], v130
	ds_read_b128 v[14:17], v130 offset:1024
	ds_read_b128 v[76:79], v130 offset:2048
	ds_read_b128 v[80:83], v130 offset:3072
	s_add_u32 s10, s40, 0x10180
	s_addc_u32 s11, s41, 0
	s_mov_b32 m0, s97
	v_lshl_add_u64 v[120:121], s[10:11], 0, v[68:69]
	ds_read_b128 v[84:87], v71
	ds_read_b128 v[92:95], v71 offset:1024
	ds_read_b128 v[96:99], v71 offset:2048
	ds_read_b128 v[100:103], v71 offset:3072
	ds_read_b128 v[104:107], v71 offset:4096
	ds_read_b128 v[108:111], v71 offset:5120
	ds_read_b128 v[112:115], v71 offset:6144
	ds_read_b128 v[116:119], v71 offset:7168
	global_load_lds_dwordx4 v[120:121], off
	v_lshl_add_u64 v[120:121], s[10:11], 0, v[66:67]
	s_mov_b32 m0, s13
	s_nop 0
	global_load_lds_dwordx4 v[120:121], off
	s_waitcnt vmcnt(8)
	s_waitcnt lgkmcnt(0)
	s_setprio 1
	s_barrier
	v_mfma_f32_16x16x32_bf16 v[38:41], v[10:13], v[112:115], v[38:41]
	v_mfma_f32_16x16x32_bf16 v[50:53], v[10:13], v[84:87], v[50:53]
	v_mfma_f32_16x16x32_bf16 v[18:21], v[76:79], v[84:87], v[18:21]
	v_mfma_f32_16x16x32_bf16 v[22:25], v[10:13], v[96:99], v[22:25]
	v_mfma_f32_16x16x32_bf16 v[26:29], v[76:79], v[96:99], v[26:29]
	v_mfma_f32_16x16x32_bf16 v[30:33], v[10:13], v[104:107], v[30:33]
	v_mfma_f32_16x16x32_bf16 v[34:37], v[76:79], v[104:107], v[34:37]
	v_mfma_f32_16x16x32_bf16 v[84:87], v[14:17], v[116:119], v[38:41]
	v_mfma_f32_16x16x32_bf16 v[38:41], v[76:79], v[112:115], v[42:45]
	v_mfma_f32_16x16x32_bf16 v[50:53], v[14:17], v[92:95], v[50:53]
	v_mfma_f32_16x16x32_bf16 v[18:21], v[80:83], v[92:95], v[18:21]
	v_mfma_f32_16x16x32_bf16 v[22:25], v[14:17], v[100:103], v[22:25]
	v_mfma_f32_16x16x32_bf16 v[26:29], v[80:83], v[100:103], v[26:29]
	v_mfma_f32_16x16x32_bf16 v[30:33], v[14:17], v[108:111], v[30:33]
	v_mfma_f32_16x16x32_bf16 v[34:37], v[80:83], v[108:111], v[34:37]
	v_mfma_f32_16x16x32_bf16 v[42:45], v[80:83], v[116:119], v[38:41]
	s_barrier
; #define PG8_STAGE(bufoff, gbase, voff) do { _Pragma("unroll") for (int _i = 0; _i < 2; ++_i) \
;         __builtin_amdgcn_global_load_lds((const unsigned*)((const char*)(gbase) + (voff)[_i]), (LAS unsigned*)(lds + (bufoff) + ldsw + _i * 8192), 16, 0, 0); } while (0)
; #define PG8_LDA(dst, b, h) do { _Pragma("unroll") for (int m = 0; m < 4; ++m) _Pragma("unroll") for (int k = 0; k < 2; ++k) dst[m][k] = *(const LAS bf16x8*)(lds + PG8_SA(b, h) + aoff + m * 2048 + k * 1024); } while (0)
; #define PG8_LDB(dst, b, h) do { _Pragma("unroll") for (int n = 0; n < 2; ++n) _Pragma("unroll") for (int k = 0; k < 2; ++k) dst[n][k] = *(const LAS bf16x8*)(lds + PG8_SB(b, h) + boff + n * 2048 + k * 1024); } while (0)
; #define PG8_MMA(ai, bj, At, Bt) do { __builtin_amdgcn_s_setprio(1); _Pragma("unroll") for (int m = 0; m < 4; ++m) _Pragma("unroll") for (int n = 0; n < 2; ++n) _Pragma("unroll") for (int k = 0; k < 2; ++k) \
;         acc[ai][bj][m][n] = __builtin_amdgcn_mfma_f32_16x16x32_bf16(Bt[n][k], At[m][k], acc[ai][bj][m][n], 0, 0, 0); __builtin_amdgcn_s_setprio(0); } while (0)
; #define PG8_WAIT_V(n) asm volatile("s_waitcnt vmcnt(" #n ")" ::: "memory")
; template <class Epi, class Sched>
; __device__ __forceinline__ void gemm_phase(LAS unsigned char* lds, const Gemm g, const Sched S, const Epi E, const int tid) {
;     ...
;             PG8_LDB(B0, 0, 0); PG8_LDB(B1, 0, 1); PG8_SCHED; PG8_LDA(At, 0, 0); PG8_STAGE(PG8_SA(1, 1), a1 + hstepA, voffA);
;             PG8_WAIT_V(8); PG8_WAIT_L(0); PG8_BAR; PG8_MMA(0, 0, At, B0); PG8_MMA(0, 1, At, B1); PG8_BAR; PG8_SCHED;
;             PG8_LDA(At, 0, 1); PG8_STAGE(PG8_SB(0, 0), b2, voffB); PG8_STAGE(PG8_SB(0, 1), b2 + hstepB, voffB); PG8_STAGE(PG8_SA(0, 0), a2, voffA);
;             PG8_WAIT_V(8); PG8_WAIT_L(0); PG8_BAR; PG8_MMA(1, 0, At, B0); PG8_MMA(1, 1, At, B1); PG8_BAR; PG8_SCHED;
;             PG8_LDB(B0, 1, 0); PG8_LDB(B1, 1, 1); PG8_SCHED; PG8_LDA(At, 1, 0); PG8_STAGE(PG8_SA(0, 1), a2 + hstepA, voffA);
;             PG8_WAIT_V(8); PG8_WAIT_L(0); PG8_BAR; PG8_MMA(0, 0, At, B0); PG8_MMA(0, 1, At, B1); PG8_BAR; PG8_SCHED;
;             PG8_LDA(At, 1, 1); PG8_STAGE(PG8_SB(1, 0), b3, voffB); PG8_STAGE(PG8_SB(1, 1), b3 + hstepB, voffB); PG8_STAGE(PG8_SA(1, 0), a3, voffA);
;             PG8_WAIT_V(8); PG8_WAIT_L(0); PG8_BAR; PG8_MMA(1, 0, At, B0); PG8_MMA(1, 1, At, B1); PG8_BAR; PG8_SCHED;
;         }
;         if (wr == 0) PG8_BAR;
	s_setprio 0
	s_mov_b32 m0, s96
	v_lshl_add_u64 v[132:133], s[26:27], 0, v[68:69]
	s_add_u32 s10, s26, 0x10000
	ds_read_b128 v[38:41], v71 offset:16384
	ds_read_b128 v[92:95], v71 offset:17408
	ds_read_b128 v[96:99], v71 offset:18432
	ds_read_b128 v[100:103], v71 offset:19456
	ds_read_b128 v[104:107], v71 offset:20480
	ds_read_b128 v[108:111], v71 offset:21504
	ds_read_b128 v[112:115], v71 offset:22528
	ds_read_b128 v[116:119], v71 offset:23552
	global_load_lds_dwordx4 v[132:133], off
	v_lshl_add_u64 v[134:135], s[26:27], 0, v[66:67]
	s_mov_b32 m0, s94
	s_addc_u32 s11, s27, 0
	global_load_lds_dwordx4 v[134:135], off
	v_lshl_add_u64 v[120:121], s[10:11], 0, v[68:69]
	s_mov_b32 m0, s48
	v_lshl_add_u64 v[136:137], s[28:29], 0, v[68:69]
	global_load_lds_dwordx4 v[120:121], off
	v_lshl_add_u64 v[120:121], s[10:11], 0, v[66:67]
	s_mov_b32 m0, s49
	v_lshl_add_u64 v[138:139], s[28:29], 0, v[66:67]
	global_load_lds_dwordx4 v[120:121], off
	s_mov_b32 m0, s37
	s_nop 0
	global_load_lds_dwordx4 v[136:137], off
	s_mov_b32 m0, s62
	s_nop 0
	global_load_lds_dwordx4 v[138:139], off
	s_waitcnt vmcnt(8)
	s_waitcnt lgkmcnt(0)
	s_setprio 1
	s_barrier
	v_mfma_f32_16x16x32_bf16 v[88:91], v[10:13], v[38:41], v[88:91]
	v_mfma_f32_16x16x32_bf16 v[38:41], v[76:79], v[38:41], v[46:49]
	v_mfma_f32_16x16x32_bf16 v[88:91], v[14:17], v[92:95], v[88:91]
	v_mfma_f32_16x16x32_bf16 v[92:95], v[80:83], v[92:95], v[38:41]
	v_mfma_f32_16x16x32_bf16 v[38:41], v[10:13], v[96:99], v[54:57]
	v_mfma_f32_16x16x32_bf16 v[120:123], v[14:17], v[100:103], v[38:41]
	v_mfma_f32_16x16x32_bf16 v[38:41], v[76:79], v[96:99], v[58:61]
	v_mfma_f32_16x16x32_bf16 v[96:99], v[80:83], v[100:103], v[38:41]
	v_mfma_f32_16x16x32_bf16 v[38:41], v[10:13], v[104:107], v[62:65]
	v_mfma_f32_16x16x32_bf16 v[2:5], v[10:13], v[112:115], v[2:5]
	v_mfma_f32_16x16x32_bf16 v[100:103], v[14:17], v[108:111], v[38:41]
	v_mfma_f32_16x16x32_bf16 v[38:41], v[76:79], v[104:107], v[72:75]
	v_mfma_f32_16x16x32_bf16 v[2:5], v[14:17], v[116:119], v[2:5]
	v_mfma_f32_16x16x32_bf16 v[6:9], v[76:79], v[112:115], v[6:9]
	v_mfma_f32_16x16x32_bf16 v[72:75], v[80:83], v[108:111], v[38:41]
	v_mfma_f32_16x16x32_bf16 v[76:79], v[80:83], v[116:119], v[6:9]
	s_barrier
	s_setprio 0
	s_nop 1
	ds_read_b128 v[6:9], v131
	ds_read_b128 v[80:83], v131 offset:1024
	ds_read_b128 v[104:107], v131 offset:2048
	ds_read_b128 v[108:111], v131 offset:3072
	s_add_u32 s10, s28, 0x10000
	s_addc_u32 s11, s29, 0
	s_mov_b32 m0, s68
	v_lshl_add_u64 v[54:55], s[10:11], 0, v[68:69]
	ds_read_b128 v[10:13], v71 offset:32768
	ds_read_b128 v[14:17], v71 offset:33792
	ds_read_b128 v[38:41], v71 offset:34816
	ds_read_b128 v[46:49], v71 offset:35840
	ds_read_b128 v[112:115], v71 offset:36864
	ds_read_b128 v[116:119], v71 offset:37888
	ds_read_b128 v[124:127], v71 offset:38912
	ds_read_b128 v[128:131], v71 offset:39936
	global_load_lds_dwordx4 v[54:55], off
	v_lshl_add_u64 v[54:55], s[10:11], 0, v[66:67]
	s_mov_b32 m0, s69
	s_nop 0
	global_load_lds_dwordx4 v[54:55], off
	s_waitcnt vmcnt(8)
	s_waitcnt lgkmcnt(0)
	s_setprio 1
	s_barrier
	v_mfma_f32_16x16x32_bf16 v[50:53], v[6:9], v[10:13], v[50:53]
	v_mfma_f32_16x16x32_bf16 v[10:13], v[104:107], v[10:13], v[18:21]
	v_mfma_f32_16x16x32_bf16 v[58:61], v[108:111], v[14:17], v[10:13]
	v_mfma_f32_16x16x32_bf16 v[10:13], v[6:9], v[38:41], v[22:25]
	v_mfma_f32_16x16x32_bf16 v[54:57], v[80:83], v[46:49], v[10:13]
	v_mfma_f32_16x16x32_bf16 v[10:13], v[104:107], v[38:41], v[26:29]
	v_mfma_f32_16x16x32_bf16 v[62:65], v[80:83], v[14:17], v[50:53]
	v_mfma_f32_16x16x32_bf16 v[50:53], v[108:111], v[46:49], v[10:13]
	v_mfma_f32_16x16x32_bf16 v[10:13], v[6:9], v[112:115], v[30:33]
	v_mfma_f32_16x16x32_bf16 v[46:49], v[80:83], v[116:119], v[10:13]
	v_mfma_f32_16x16x32_bf16 v[10:13], v[104:107], v[112:115], v[34:37]
	v_mfma_f32_16x16x32_bf16 v[38:41], v[108:111], v[116:119], v[10:13]
	v_mfma_f32_16x16x32_bf16 v[10:13], v[6:9], v[124:127], v[84:87]
	v_mfma_f32_16x16x32_bf16 v[30:33], v[80:83], v[128:131], v[10:13]
	v_mfma_f32_16x16x32_bf16 v[10:13], v[104:107], v[124:127], v[42:45]
	v_mfma_f32_16x16x32_bf16 v[22:25], v[108:111], v[128:131], v[10:13]
	s_barrier
	s_setprio 0
	s_mov_b32 m0, vcc_lo
	v_lshl_add_u64 v[26:27], v[132:133], 0, s[64:65]
	s_add_u32 s10, s26, 0x10080
	ds_read_b128 v[10:13], v71 offset:49152
	ds_read_b128 v[14:17], v71 offset:50176
	ds_read_b128 v[18:21], v71 offset:51200
	ds_read_b128 v[84:87], v71 offset:52224
	ds_read_b128 v[112:115], v71 offset:53248
	ds_read_b128 v[116:119], v71 offset:54272
	ds_read_b128 v[124:127], v71 offset:55296
	ds_read_b128 v[128:131], v71 offset:56320
	global_load_lds_dwordx4 v[26:27], off
	v_lshl_add_u64 v[26:27], v[134:135], 0, s[64:65]
	s_mov_b32 m0, s95
	s_addc_u32 s11, s27, 0
	global_load_lds_dwordx4 v[26:27], off
	v_lshl_add_u64 v[26:27], s[10:11], 0, v[68:69]
	s_mov_b32 m0, s85
	s_nop 0
	global_load_lds_dwordx4 v[26:27], off
	v_lshl_add_u64 v[26:27], s[10:11], 0, v[66:67]
	s_mov_b32 m0, s88
	s_nop 0
	global_load_lds_dwordx4 v[26:27], off
	v_lshl_add_u64 v[26:27], v[136:137], 0, s[64:65]
	s_mov_b32 m0, s83
	s_nop 0
	global_load_lds_dwordx4 v[26:27], off
	v_lshl_add_u64 v[26:27], v[138:139], 0, s[64:65]
	s_mov_b32 m0, s84
	s_nop 0
	global_load_lds_dwordx4 v[26:27], off
	s_waitcnt vmcnt(8)
	s_waitcnt lgkmcnt(0)
	s_setprio 1
	s_barrier
	v_mfma_f32_16x16x32_bf16 v[26:29], v[6:9], v[10:13], v[88:91]
	v_mfma_f32_16x16x32_bf16 v[10:13], v[104:107], v[10:13], v[92:95]
	v_mfma_f32_16x16x32_bf16 v[34:37], v[108:111], v[14:17], v[10:13]
	v_mfma_f32_16x16x32_bf16 v[10:13], v[6:9], v[18:21], v[120:123]
	v_mfma_f32_16x16x32_bf16 v[42:45], v[80:83], v[14:17], v[26:29]
	v_mfma_f32_16x16x32_bf16 v[26:29], v[80:83], v[84:87], v[10:13]
	v_mfma_f32_16x16x32_bf16 v[10:13], v[104:107], v[18:21], v[96:99]
	v_mfma_f32_16x16x32_bf16 v[18:21], v[108:111], v[84:87], v[10:13]
	v_mfma_f32_16x16x32_bf16 v[10:13], v[6:9], v[112:115], v[100:103]
	v_mfma_f32_16x16x32_bf16 v[2:5], v[6:9], v[124:127], v[2:5]
	v_mfma_f32_16x16x32_bf16 v[14:17], v[80:83], v[116:119], v[10:13]
	v_mfma_f32_16x16x32_bf16 v[10:13], v[104:107], v[112:115], v[72:75]
	v_mfma_f32_16x16x32_bf16 v[6:9], v[80:83], v[128:131], v[2:5]
	v_mfma_f32_16x16x32_bf16 v[2:5], v[104:107], v[124:127], v[76:79]
	v_mfma_f32_16x16x32_bf16 v[10:13], v[108:111], v[116:119], v[10:13]
	v_mfma_f32_16x16x32_bf16 v[2:5], v[108:111], v[128:131], v[2:5]
	s_barrier
	s_setprio 0
	s_andn2_b64 vcc, exec, s[18:19]
	s_cbranch_vccnz .LBB0_312
	s_barrier

; #define PG8_STAGE(bufoff, gbase, voff) do { _Pragma("unroll") for (int _i = 0; _i < 2; ++_i) \
;         __builtin_amdgcn_global_load_lds((const unsigned*)((const char*)(gbase) + (voff)[_i]), (LAS unsigned*)(lds + (bufoff) + ldsw + _i * 8192), 16, 0, 0); } while (0)
; #define PG8_LDA(dst, b, h) do { _Pragma("unroll") for (int m = 0; m < 4; ++m) _Pragma("unroll") for (int k = 0; k < 2; ++k) dst[m][k] = *(const LAS bf16x8*)(lds + PG8_SA(b, h) + aoff + m * 2048 + k * 1024); } while (0)
; #define PG8_LDB(dst, b, h) do { _Pragma("unroll") for (int n = 0; n < 2; ++n) _Pragma("unroll") for (int k = 0; k < 2; ++k) dst[n][k] = *(const LAS bf16x8*)(lds + PG8_SB(b, h) + boff + n * 2048 + k * 1024); } while (0)
; #define PG8_WAIT_V(n) asm volatile("s_waitcnt vmcnt(" #n ")" ::: "memory")
; #define PG8_BAR __builtin_amdgcn_s_barrier()
; template <class Epi, class Sched>
; __device__ __forceinline__ void gemm_phase(LAS unsigned char* lds, const Gemm g, const Sched S, const Epi E, const int tid) {
;     ...
;         for (int t = 0; t < nt; t += 2) {
;             const bool last = (t == nt - 2);
;             const char* a1 = cA + (size_t)(t + 1) * kstep;
;             const char* a2 = last ? nA : cA + (size_t)(t + 2) * kstep; const char* b2 = last ? nB : cB + (size_t)(t + 2) * kstep;
;             const char* a3 = a2 + kstep; const char* b3 = b2 + kstep;
;             PG8_LDB(B0, 0, 0); PG8_LDB(B1, 0, 1); PG8_SCHED; PG8_LDA(At, 0, 0); PG8_STAGE(PG8_SA(1, 1), a1 + hstepA, voffA);
;             PG8_WAIT_V(8); PG8_WAIT_L(0); PG8_BAR; PG8_MMA(0, 0, At, B0); PG8_MMA(0, 1, At, B1); PG8_BAR; PG8_SCHED;
;             PG8_LDA(At, 0, 1); PG8_STAGE(PG8_SB(0, 0), b2, voffB); PG8_STAGE(PG8_SB(0, 1), b2 + hstepB, voffB); PG8_STAGE(PG8_SA(0, 0), a2, voffA);
;             PG8_WAIT_V(8); PG8_WAIT_L(0); PG8_BAR; PG8_MMA(1, 0, At, B0); PG8_MMA(1, 1, At, B1); PG8_BAR; PG8_SCHED;
;             PG8_LDB(B0, 1, 0); PG8_LDB(B1, 1, 1); PG8_SCHED; PG8_LDA(At, 1, 0); PG8_STAGE(PG8_SA(0, 1), a2 + hstepA, voffA);
;             PG8_WAIT_V(8); PG8_WAIT_L(0); PG8_BAR; PG8_MMA(0, 0, At, B0); PG8_MMA(0, 1, At, B1); PG8_BAR; PG8_SCHED;
;             PG8_LDA(At, 1, 1); PG8_STAGE(PG8_SB(1, 0), b3, voffB); PG8_STAGE(PG8_SB(1, 1), b3 + hstepB, voffB); PG8_STAGE(PG8_SA(1, 0), a3, voffA);
;             PG8_WAIT_V(8); PG8_WAIT_L(0); PG8_BAR; PG8_MMA(1, 0, At, B0); PG8_MMA(1, 1, At, B1); PG8_BAR; PG8_SCHED;
.LBB0_332:
	s_add_u32 s10, s44, 0xfffc0080
	s_addc_u32 s11, s45, -1
	s_add_i32 vcc_lo, 0, 0x10000
	s_cmp_eq_u32 s97, 12
	s_cselect_b32 s83, s7, s11
	s_cselect_b32 s82, s92, s10
	v_add_u32_e32 v154, vcc_lo, v157
	s_cselect_b32 s47, s93, s96
	s_cselect_b32 s46, s94, s95
	s_add_i32 vcc_hi, 0, 0x14000
	s_waitcnt lgkmcnt(0)
	ds_read_b128 v[130:133], v154
	ds_read_b128 v[134:137], v154 offset:1024
	ds_read_b128 v[150:153], v154 offset:2048
	ds_read_b128 v[160:163], v154 offset:3072
	v_add_u32_e32 v154, vcc_hi, v157
	ds_read_b128 v[164:167], v154
	ds_read_b128 v[180:183], v154 offset:1024
	ds_read_b128 v[184:187], v154 offset:2048
	ds_read_b128 v[188:191], v154 offset:3072
	v_lshl_add_u64 v[154:155], s[44:45], 0, v[148:149]
	s_add_i32 m0, s48, 0xc000
	ds_read_b128 v[192:195], v158
	ds_read_b128 v[196:199], v158 offset:1024
	ds_read_b128 v[200:203], v158 offset:2048
	ds_read_b128 v[204:207], v158 offset:3072
	ds_read_b128 v[208:211], v158 offset:4096
	ds_read_b128 v[212:215], v158 offset:5120
	ds_read_b128 v[216:219], v158 offset:6144
	ds_read_b128 v[220:223], v158 offset:7168
	global_load_lds_dwordx4 v[154:155], off
	v_lshl_add_u64 v[154:155], s[44:45], 0, v[146:147]
	s_add_i32 m0, s48, 0xe000
	s_nop 0
	global_load_lds_dwordx4 v[154:155], off
	s_waitcnt vmcnt(8)
	s_waitcnt lgkmcnt(0)
	s_setprio 1
	s_barrier
	v_mfma_f32_16x16x32_bf16 v[122:125], v[130:133], v[192:195], v[122:125]
	v_mfma_f32_16x16x32_bf16 v[114:117], v[150:153], v[192:195], v[114:117]
	v_mfma_f32_16x16x32_bf16 v[106:109], v[130:133], v[200:203], v[106:109]
	v_mfma_f32_16x16x32_bf16 v[98:101], v[150:153], v[200:203], v[98:101]
	v_mfma_f32_16x16x32_bf16 v[90:93], v[130:133], v[208:211], v[90:93]
	v_mfma_f32_16x16x32_bf16 v[82:85], v[150:153], v[208:211], v[82:85]
	v_mfma_f32_16x16x32_bf16 v[74:77], v[130:133], v[216:219], v[74:77]
	v_mfma_f32_16x16x32_bf16 v[66:69], v[150:153], v[216:219], v[66:69]
	v_mfma_f32_16x16x32_bf16 v[122:125], v[134:137], v[196:199], v[122:125]
	v_mfma_f32_16x16x32_bf16 v[114:117], v[160:163], v[196:199], v[114:117]
	v_mfma_f32_16x16x32_bf16 v[106:109], v[134:137], v[204:207], v[106:109]
	v_mfma_f32_16x16x32_bf16 v[98:101], v[160:163], v[204:207], v[98:101]
	v_mfma_f32_16x16x32_bf16 v[90:93], v[134:137], v[212:215], v[90:93]
	v_mfma_f32_16x16x32_bf16 v[82:85], v[160:163], v[212:215], v[82:85]
	v_mfma_f32_16x16x32_bf16 v[74:77], v[134:137], v[220:223], v[74:77]
	v_mfma_f32_16x16x32_bf16 v[66:69], v[160:163], v[220:223], v[66:69]
	v_mfma_f32_16x16x32_bf16 v[126:129], v[164:167], v[192:195], v[126:129]
	v_mfma_f32_16x16x32_bf16 v[118:121], v[184:187], v[192:195], v[118:121]
	v_mfma_f32_16x16x32_bf16 v[110:113], v[164:167], v[200:203], v[110:113]
	v_mfma_f32_16x16x32_bf16 v[102:105], v[184:187], v[200:203], v[102:105]
	v_mfma_f32_16x16x32_bf16 v[94:97], v[164:167], v[208:211], v[94:97]
	v_mfma_f32_16x16x32_bf16 v[86:89], v[184:187], v[208:211], v[86:89]
	v_mfma_f32_16x16x32_bf16 v[78:81], v[164:167], v[216:219], v[78:81]
	v_mfma_f32_16x16x32_bf16 v[70:73], v[184:187], v[216:219], v[70:73]
	v_mfma_f32_16x16x32_bf16 v[126:129], v[180:183], v[196:199], v[126:129]
	v_mfma_f32_16x16x32_bf16 v[118:121], v[188:191], v[196:199], v[118:121]
	v_mfma_f32_16x16x32_bf16 v[110:113], v[180:183], v[204:207], v[110:113]
	v_mfma_f32_16x16x32_bf16 v[102:105], v[188:191], v[204:207], v[102:105]
	v_mfma_f32_16x16x32_bf16 v[94:97], v[180:183], v[212:215], v[94:97]
	v_mfma_f32_16x16x32_bf16 v[86:89], v[188:191], v[212:215], v[86:89]
	v_mfma_f32_16x16x32_bf16 v[78:81], v[180:183], v[220:223], v[78:81]
	v_mfma_f32_16x16x32_bf16 v[70:73], v[188:191], v[220:223], v[70:73]
	s_barrier
	s_setprio 0
	s_add_i32 s10, vcc_lo, s37
	v_lshl_add_u64 v[154:155], s[46:47], 0, v[140:141]
	s_mov_b32 m0, s10
	ds_read_b128 v[192:195], v158 offset:16384
	ds_read_b128 v[196:199], v158 offset:17408
	ds_read_b128 v[200:203], v158 offset:18432
	ds_read_b128 v[204:207], v158 offset:19456
	ds_read_b128 v[208:211], v158 offset:20480
	ds_read_b128 v[212:215], v158 offset:21504
	ds_read_b128 v[216:219], v158 offset:22528
	ds_read_b128 v[220:223], v158 offset:23552
	global_load_lds_dwordx4 v[154:155], off
	s_add_i32 m0, s10, 0x2000
	s_add_u32 s10, s46, 0x40000
	v_lshl_add_u64 v[224:225], s[46:47], 0, v[144:145]
	s_addc_u32 s11, s47, 0
	s_add_i32 vcc_lo, vcc_hi, s37
	global_load_lds_dwordx4 v[224:225], off
	v_lshl_add_u64 v[226:227], s[10:11], 0, v[140:141]
	s_mov_b32 m0, vcc_lo
	v_lshl_add_u64 v[228:229], s[82:83], 0, v[142:143]
	global_load_lds_dwordx4 v[226:227], off
	v_lshl_add_u64 v[226:227], s[10:11], 0, v[144:145]
	s_add_i32 m0, vcc_lo, 0x2000
	s_nop 0
	global_load_lds_dwordx4 v[226:227], off
	v_lshl_add_u64 v[226:227], s[82:83], 0, v[138:139]
	s_mov_b32 m0, s48
	s_nop 0
	global_load_lds_dwordx4 v[226:227], off
	s_mov_b32 m0, s49
	s_nop 0
	global_load_lds_dwordx4 v[228:229], off
	s_waitcnt vmcnt(8)
	s_waitcnt lgkmcnt(0)
	s_setprio 1
	s_barrier
; #define PG8_STAGE(bufoff, gbase, voff) do { _Pragma("unroll") for (int _i = 0; _i < 2; ++_i) \
;         __builtin_amdgcn_global_load_lds((const unsigned*)((const char*)(gbase) + (voff)[_i]), (LAS unsigned*)(lds + (bufoff) + ldsw + _i * 8192), 16, 0, 0); } while (0)
; #define PG8_LDA(dst, b, h) do { _Pragma("unroll") for (int m = 0; m < 4; ++m) _Pragma("unroll") for (int k = 0; k < 2; ++k) dst[m][k] = *(const LAS bf16x8*)(lds + PG8_SA(b, h) + aoff + m * 2048 + k * 1024); } while (0)
; #define PG8_LDB(dst, b, h) do { _Pragma("unroll") for (int n = 0; n < 2; ++n) _Pragma("unroll") for (int k = 0; k < 2; ++k) dst[n][k] = *(const LAS bf16x8*)(lds + PG8_SB(b, h) + boff + n * 2048 + k * 1024); } while (0)
; #define PG8_MMA(ai, bj, At, Bt) do { __builtin_amdgcn_s_setprio(1); _Pragma("unroll") for (int m = 0; m < 4; ++m) _Pragma("unroll") for (int n = 0; n < 2; ++n) _Pragma("unroll") for (int k = 0; k < 2; ++k) \
;         acc[ai][bj][m][n] = __builtin_amdgcn_mfma_f32_16x16x32_bf16(Bt[n][k], At[m][k], acc[ai][bj][m][n], 0, 0, 0); __builtin_amdgcn_s_setprio(0); } while (0)
; #define PG8_WAIT_V(n) asm volatile("s_waitcnt vmcnt(" #n ")" ::: "memory")
; #define PG8_WAIT_L(n) asm volatile("s_waitcnt lgkmcnt(" #n ")" ::: "memory")
; #define PG8_BAR __builtin_amdgcn_s_barrier()
; #define PG8_SCHED __builtin_amdgcn_sched_barrier(0)
; template <class Epi, class Sched>
; __device__ __forceinline__ void gemm_phase(LAS unsigned char* lds, const Gemm g, const Sched S, const Epi E, const int tid) {
;     ...
;             PG8_WAIT_V(8); PG8_WAIT_L(0); PG8_BAR; PG8_MMA(0, 0, At, B0); PG8_MMA(0, 1, At, B1); PG8_BAR; PG8_SCHED;
;             PG8_LDA(At, 0, 1); PG8_STAGE(PG8_SB(0, 0), b2, voffB); PG8_STAGE(PG8_SB(0, 1), b2 + hstepB, voffB); PG8_STAGE(PG8_SA(0, 0), a2, voffA);
;             PG8_WAIT_V(8); PG8_WAIT_L(0); PG8_BAR; PG8_MMA(1, 0, At, B0); PG8_MMA(1, 1, At, B1); PG8_BAR; PG8_SCHED;
;             PG8_LDB(B0, 1, 0); PG8_LDB(B1, 1, 1); PG8_SCHED; PG8_LDA(At, 1, 0); PG8_STAGE(PG8_SA(0, 1), a2 + hstepA, voffA);
;             PG8_WAIT_V(8); PG8_WAIT_L(0); PG8_BAR; PG8_MMA(0, 0, At, B0); PG8_MMA(0, 1, At, B1); PG8_BAR; PG8_SCHED;
	v_mfma_f32_16x16x32_bf16 v[58:61], v[130:133], v[192:195], v[58:61]
	v_mfma_f32_16x16x32_bf16 v[50:53], v[150:153], v[192:195], v[50:53]
	v_mfma_f32_16x16x32_bf16 v[42:45], v[130:133], v[200:203], v[42:45]
	v_mfma_f32_16x16x32_bf16 v[34:37], v[150:153], v[200:203], v[34:37]
	v_mfma_f32_16x16x32_bf16 v[26:29], v[130:133], v[208:211], v[26:29]
	v_mfma_f32_16x16x32_bf16 v[18:21], v[150:153], v[208:211], v[18:21]
	v_mfma_f32_16x16x32_bf16 v[10:13], v[130:133], v[216:219], v[10:13]
	v_mfma_f32_16x16x32_bf16 v[6:9], v[150:153], v[216:219], v[6:9]
	v_mfma_f32_16x16x32_bf16 v[58:61], v[134:137], v[196:199], v[58:61]
	v_mfma_f32_16x16x32_bf16 v[50:53], v[160:163], v[196:199], v[50:53]
	v_mfma_f32_16x16x32_bf16 v[42:45], v[134:137], v[204:207], v[42:45]
	v_mfma_f32_16x16x32_bf16 v[34:37], v[160:163], v[204:207], v[34:37]
	v_mfma_f32_16x16x32_bf16 v[26:29], v[134:137], v[212:215], v[26:29]
	v_mfma_f32_16x16x32_bf16 v[18:21], v[160:163], v[212:215], v[18:21]
	v_mfma_f32_16x16x32_bf16 v[10:13], v[134:137], v[220:223], v[10:13]
	v_mfma_f32_16x16x32_bf16 v[6:9], v[160:163], v[220:223], v[6:9]
	v_mfma_f32_16x16x32_bf16 v[62:65], v[164:167], v[192:195], v[62:65]
	v_mfma_f32_16x16x32_bf16 v[54:57], v[184:187], v[192:195], v[54:57]
	v_mfma_f32_16x16x32_bf16 v[46:49], v[164:167], v[200:203], v[46:49]
	v_mfma_f32_16x16x32_bf16 v[38:41], v[184:187], v[200:203], v[38:41]
	v_mfma_f32_16x16x32_bf16 v[30:33], v[164:167], v[208:211], v[30:33]
	v_mfma_f32_16x16x32_bf16 v[22:25], v[184:187], v[208:211], v[22:25]
	v_mfma_f32_16x16x32_bf16 v[14:17], v[164:167], v[216:219], v[14:17]
	v_mfma_f32_16x16x32_bf16 v[2:5], v[184:187], v[216:219], v[2:5]
	v_mfma_f32_16x16x32_bf16 v[62:65], v[180:183], v[196:199], v[62:65]
	v_mfma_f32_16x16x32_bf16 v[54:57], v[188:191], v[196:199], v[54:57]
	v_mfma_f32_16x16x32_bf16 v[46:49], v[180:183], v[204:207], v[46:49]
	v_mfma_f32_16x16x32_bf16 v[38:41], v[188:191], v[204:207], v[38:41]
	v_mfma_f32_16x16x32_bf16 v[30:33], v[180:183], v[212:215], v[30:33]
	v_mfma_f32_16x16x32_bf16 v[22:25], v[188:191], v[212:215], v[22:25]
	v_mfma_f32_16x16x32_bf16 v[14:17], v[180:183], v[220:223], v[14:17]
	v_mfma_f32_16x16x32_bf16 v[2:5], v[188:191], v[220:223], v[2:5]
	s_barrier
	s_setprio 0
	s_add_i32 vcc_lo, 0, 0x18000
	v_add_u32_e32 v159, vcc_lo, v157
	s_add_i32 vcc_hi, 0, 0x1c000
	ds_read_b128 v[130:133], v159
	ds_read_b128 v[134:137], v159 offset:1024
	ds_read_b128 v[150:153], v159 offset:2048
	ds_read_b128 v[160:163], v159 offset:3072
	v_add_u32_e32 v159, vcc_hi, v157
	ds_read_b128 v[164:167], v159
	ds_read_b128 v[180:183], v159 offset:1024
	ds_read_b128 v[184:187], v159 offset:2048
	ds_read_b128 v[188:191], v159 offset:3072
	s_add_u32 s10, s82, 0x40000
	s_addc_u32 s11, s83, 0
	s_mov_b32 m0, s62
	v_lshl_add_u64 v[230:231], s[10:11], 0, v[138:139]
	ds_read_b128 v[192:195], v158 offset:32768
	ds_read_b128 v[196:199], v158 offset:33792
	ds_read_b128 v[200:203], v158 offset:34816
	ds_read_b128 v[204:207], v158 offset:35840
	ds_read_b128 v[208:211], v158 offset:36864
	ds_read_b128 v[212:215], v158 offset:37888
	ds_read_b128 v[216:219], v158 offset:38912
	ds_read_b128 v[220:223], v158 offset:39936
	global_load_lds_dwordx4 v[230:231], off
	v_lshl_add_u64 v[230:231], s[10:11], 0, v[142:143]
	s_mov_b32 m0, s68
	s_nop 0
	global_load_lds_dwordx4 v[230:231], off
	s_waitcnt vmcnt(8)
	s_waitcnt lgkmcnt(0)
	s_setprio 1
	s_barrier
	v_mfma_f32_16x16x32_bf16 v[122:125], v[130:133], v[192:195], v[122:125]
	v_mfma_f32_16x16x32_bf16 v[114:117], v[150:153], v[192:195], v[114:117]
	v_mfma_f32_16x16x32_bf16 v[106:109], v[130:133], v[200:203], v[106:109]
	v_mfma_f32_16x16x32_bf16 v[98:101], v[150:153], v[200:203], v[98:101]
	v_mfma_f32_16x16x32_bf16 v[90:93], v[130:133], v[208:211], v[90:93]
	v_mfma_f32_16x16x32_bf16 v[82:85], v[150:153], v[208:211], v[82:85]
	v_mfma_f32_16x16x32_bf16 v[74:77], v[130:133], v[216:219], v[74:77]
	v_mfma_f32_16x16x32_bf16 v[66:69], v[150:153], v[216:219], v[66:69]
	v_mfma_f32_16x16x32_bf16 v[122:125], v[134:137], v[196:199], v[122:125]
	v_mfma_f32_16x16x32_bf16 v[114:117], v[160:163], v[196:199], v[114:117]
	v_mfma_f32_16x16x32_bf16 v[106:109], v[134:137], v[204:207], v[106:109]
	v_mfma_f32_16x16x32_bf16 v[98:101], v[160:163], v[204:207], v[98:101]
	v_mfma_f32_16x16x32_bf16 v[90:93], v[134:137], v[212:215], v[90:93]
	v_mfma_f32_16x16x32_bf16 v[82:85], v[160:163], v[212:215], v[82:85]
	v_mfma_f32_16x16x32_bf16 v[74:77], v[134:137], v[220:223], v[74:77]
	v_mfma_f32_16x16x32_bf16 v[66:69], v[160:163], v[220:223], v[66:69]
	v_mfma_f32_16x16x32_bf16 v[126:129], v[164:167], v[192:195], v[126:129]
	v_mfma_f32_16x16x32_bf16 v[118:121], v[184:187], v[192:195], v[118:121]
	v_mfma_f32_16x16x32_bf16 v[110:113], v[164:167], v[200:203], v[110:113]
	v_mfma_f32_16x16x32_bf16 v[102:105], v[184:187], v[200:203], v[102:105]
	v_mfma_f32_16x16x32_bf16 v[94:97], v[164:167], v[208:211], v[94:97]
	v_mfma_f32_16x16x32_bf16 v[86:89], v[184:187], v[208:211], v[86:89]
	v_mfma_f32_16x16x32_bf16 v[78:81], v[164:167], v[216:219], v[78:81]
	v_mfma_f32_16x16x32_bf16 v[70:73], v[184:187], v[216:219], v[70:73]
	v_mfma_f32_16x16x32_bf16 v[126:129], v[180:183], v[196:199], v[126:129]
	v_mfma_f32_16x16x32_bf16 v[118:121], v[188:191], v[196:199], v[118:121]
	v_mfma_f32_16x16x32_bf16 v[110:113], v[180:183], v[204:207], v[110:113]
	v_mfma_f32_16x16x32_bf16 v[102:105], v[188:191], v[204:207], v[102:105]
	v_mfma_f32_16x16x32_bf16 v[94:97], v[180:183], v[212:215], v[94:97]
	v_mfma_f32_16x16x32_bf16 v[86:89], v[188:191], v[212:215], v[86:89]
	v_mfma_f32_16x16x32_bf16 v[78:81], v[180:183], v[220:223], v[78:81]
	v_mfma_f32_16x16x32_bf16 v[70:73], v[188:191], v[220:223], v[70:73]
	s_barrier
; #define PG8_STAGE(bufoff, gbase, voff) do { _Pragma("unroll") for (int _i = 0; _i < 2; ++_i) \
;         __builtin_amdgcn_global_load_lds((const unsigned*)((const char*)(gbase) + (voff)[_i]), (LAS unsigned*)(lds + (bufoff) + ldsw + _i * 8192), 16, 0, 0); } while (0)
; #define PG8_LDA(dst, b, h) do { _Pragma("unroll") for (int m = 0; m < 4; ++m) _Pragma("unroll") for (int k = 0; k < 2; ++k) dst[m][k] = *(const LAS bf16x8*)(lds + PG8_SA(b, h) + aoff + m * 2048 + k * 1024); } while (0)
; #define PG8_MMA(ai, bj, At, Bt) do { __builtin_amdgcn_s_setprio(1); _Pragma("unroll") for (int m = 0; m < 4; ++m) _Pragma("unroll") for (int n = 0; n < 2; ++n) _Pragma("unroll") for (int k = 0; k < 2; ++k) \
;         acc[ai][bj][m][n] = __builtin_amdgcn_mfma_f32_16x16x32_bf16(Bt[n][k], At[m][k], acc[ai][bj][m][n], 0, 0, 0); __builtin_amdgcn_s_setprio(0); } while (0)
; #define PG8_WAIT_V(n) asm volatile("s_waitcnt vmcnt(" #n ")" ::: "memory")
; #define PG8_WAIT_L(n) asm volatile("s_waitcnt lgkmcnt(" #n ")" ::: "memory")
; #define PG8_BAR __builtin_amdgcn_s_barrier()
; #define PG8_SCHED __builtin_amdgcn_sched_barrier(0)
; template <class Epi, class Sched>
; __device__ __forceinline__ void gemm_phase(LAS unsigned char* lds, const Gemm g, const Sched S, const Epi E, const int tid) {
;     ...
;             PG8_LDA(At, 1, 1); PG8_STAGE(PG8_SB(1, 0), b3, voffB); PG8_STAGE(PG8_SB(1, 1), b3 + hstepB, voffB); PG8_STAGE(PG8_SA(1, 0), a3, voffA);
;             PG8_WAIT_V(8); PG8_WAIT_L(0); PG8_BAR; PG8_MMA(1, 0, At, B0); PG8_MMA(1, 1, At, B1); PG8_BAR; PG8_SCHED;
;         }
;         if (wr == 0) PG8_BAR;
	s_setprio 0
	s_add_i32 s10, vcc_lo, s37
	v_lshl_add_u64 v[154:155], v[154:155], 0, s[64:65]
	s_mov_b32 m0, s10
	ds_read_b128 v[192:195], v158 offset:49152
	ds_read_b128 v[196:199], v158 offset:50176
	ds_read_b128 v[200:203], v158 offset:51200
	ds_read_b128 v[204:207], v158 offset:52224
	ds_read_b128 v[208:211], v158 offset:53248
	ds_read_b128 v[212:215], v158 offset:54272
	ds_read_b128 v[216:219], v158 offset:55296
	ds_read_b128 v[220:223], v158 offset:56320
	global_load_lds_dwordx4 v[154:155], off
	s_add_i32 m0, s10, 0x2000
	s_add_u32 s10, s46, 0x40080
	v_lshl_add_u64 v[154:155], v[224:225], 0, s[64:65]
	s_addc_u32 s11, s47, 0
	s_add_i32 s46, vcc_hi, s37
	global_load_lds_dwordx4 v[154:155], off
	v_lshl_add_u64 v[154:155], s[10:11], 0, v[140:141]
	s_mov_b32 m0, s46
	s_nop 0
	global_load_lds_dwordx4 v[154:155], off
	v_lshl_add_u64 v[154:155], s[10:11], 0, v[144:145]
	s_add_i32 m0, s46, 0x2000
	s_nop 0
	global_load_lds_dwordx4 v[154:155], off
	v_lshl_add_u64 v[154:155], v[226:227], 0, s[64:65]
	s_mov_b32 m0, s88
	s_nop 0
	global_load_lds_dwordx4 v[154:155], off
	v_lshl_add_u64 v[154:155], v[228:229], 0, s[64:65]
	s_mov_b32 m0, s89
	s_nop 0
	global_load_lds_dwordx4 v[154:155], off
	s_waitcnt vmcnt(8)
	s_waitcnt lgkmcnt(0)
	s_setprio 1
	s_barrier
	v_mfma_f32_16x16x32_bf16 v[58:61], v[130:133], v[192:195], v[58:61]
	v_mfma_f32_16x16x32_bf16 v[50:53], v[150:153], v[192:195], v[50:53]
	v_mfma_f32_16x16x32_bf16 v[42:45], v[130:133], v[200:203], v[42:45]
	v_mfma_f32_16x16x32_bf16 v[34:37], v[150:153], v[200:203], v[34:37]
	v_mfma_f32_16x16x32_bf16 v[26:29], v[130:133], v[208:211], v[26:29]
	v_mfma_f32_16x16x32_bf16 v[18:21], v[150:153], v[208:211], v[18:21]
	v_mfma_f32_16x16x32_bf16 v[10:13], v[130:133], v[216:219], v[10:13]
	v_mfma_f32_16x16x32_bf16 v[6:9], v[150:153], v[216:219], v[6:9]
	v_mfma_f32_16x16x32_bf16 v[58:61], v[134:137], v[196:199], v[58:61]
	v_mfma_f32_16x16x32_bf16 v[50:53], v[160:163], v[196:199], v[50:53]
	v_mfma_f32_16x16x32_bf16 v[42:45], v[134:137], v[204:207], v[42:45]
	v_mfma_f32_16x16x32_bf16 v[34:37], v[160:163], v[204:207], v[34:37]
	v_mfma_f32_16x16x32_bf16 v[26:29], v[134:137], v[212:215], v[26:29]
	v_mfma_f32_16x16x32_bf16 v[18:21], v[160:163], v[212:215], v[18:21]
	v_mfma_f32_16x16x32_bf16 v[10:13], v[134:137], v[220:223], v[10:13]
	v_mfma_f32_16x16x32_bf16 v[6:9], v[160:163], v[220:223], v[6:9]
	v_mfma_f32_16x16x32_bf16 v[62:65], v[164:167], v[192:195], v[62:65]
	v_mfma_f32_16x16x32_bf16 v[54:57], v[184:187], v[192:195], v[54:57]
	v_mfma_f32_16x16x32_bf16 v[46:49], v[164:167], v[200:203], v[46:49]
	v_mfma_f32_16x16x32_bf16 v[38:41], v[184:187], v[200:203], v[38:41]
	v_mfma_f32_16x16x32_bf16 v[30:33], v[164:167], v[208:211], v[30:33]
	v_mfma_f32_16x16x32_bf16 v[22:25], v[184:187], v[208:211], v[22:25]
	v_mfma_f32_16x16x32_bf16 v[14:17], v[164:167], v[216:219], v[14:17]
	v_mfma_f32_16x16x32_bf16 v[2:5], v[184:187], v[216:219], v[2:5]
	v_mfma_f32_16x16x32_bf16 v[62:65], v[180:183], v[196:199], v[62:65]
	v_mfma_f32_16x16x32_bf16 v[54:57], v[188:191], v[196:199], v[54:57]
	v_mfma_f32_16x16x32_bf16 v[46:49], v[180:183], v[204:207], v[46:49]
	v_mfma_f32_16x16x32_bf16 v[38:41], v[188:191], v[204:207], v[38:41]
	v_mfma_f32_16x16x32_bf16 v[30:33], v[180:183], v[212:215], v[30:33]
	v_mfma_f32_16x16x32_bf16 v[22:25], v[188:191], v[212:215], v[22:25]
	v_mfma_f32_16x16x32_bf16 v[14:17], v[180:183], v[220:223], v[14:17]
	v_mfma_f32_16x16x32_bf16 v[2:5], v[188:191], v[220:223], v[2:5]
	s_barrier
	s_setprio 0
	s_add_i32 s97, s97, 2
	s_add_u32 s95, s95, 0x100
	s_addc_u32 s96, s96, 0
	s_add_u32 s44, s44, 0x100
	s_addc_u32 s45, s45, 0
	s_cmp_gt_u32 s97, 13
	s_cbranch_scc0 .LBB0_332
	s_and_b64 vcc, exec, s[14:15]
	s_cbranch_vccz .LBB0_335
	s_barrier

; #define PG8_STAGE(bufoff, gbase, voff) do { _Pragma("unroll") for (int _i = 0; _i < 2; ++_i) \
;         __builtin_amdgcn_global_load_lds((const unsigned*)((const char*)(gbase) + (voff)[_i]), (LAS unsigned*)(lds + (bufoff) + ldsw + _i * 8192), 16, 0, 0); } while (0)
; #define PG8_LDA(dst, b, h) do { _Pragma("unroll") for (int m = 0; m < 4; ++m) _Pragma("unroll") for (int k = 0; k < 2; ++k) dst[m][k] = *(const LAS bf16x8*)(lds + PG8_SA(b, h) + aoff + m * 2048 + k * 1024); } while (0)
; #define PG8_LDB(dst, b, h) do { _Pragma("unroll") for (int n = 0; n < 2; ++n) _Pragma("unroll") for (int k = 0; k < 2; ++k) dst[n][k] = *(const LAS bf16x8*)(lds + PG8_SB(b, h) + boff + n * 2048 + k * 1024); } while (0)
; #define PG8_WAIT_V(n) asm volatile("s_waitcnt vmcnt(" #n ")" ::: "memory")
; #define PG8_BAR __builtin_amdgcn_s_barrier()
; template <class Epi, class Sched>
; __device__ __forceinline__ void gemm_phase(LAS unsigned char* lds, const Gemm g, const Sched S, const Epi E, const int tid) {
;     ...
;         for (int t = 0; t < nt; t += 2) {
;             const bool last = (t == nt - 2);
;             const char* a1 = cA + (size_t)(t + 1) * kstep;
;             const char* a2 = last ? nA : cA + (size_t)(t + 2) * kstep; const char* b2 = last ? nB : cB + (size_t)(t + 2) * kstep;
;             const char* a3 = a2 + kstep; const char* b3 = b2 + kstep;
;             PG8_LDB(B0, 0, 0); PG8_LDB(B1, 0, 1); PG8_SCHED; PG8_LDA(At, 0, 0); PG8_STAGE(PG8_SA(1, 1), a1 + hstepA, voffA);
;             PG8_WAIT_V(8); PG8_WAIT_L(0); PG8_BAR; PG8_MMA(0, 0, At, B0); PG8_MMA(0, 1, At, B1); PG8_BAR; PG8_SCHED;
;             PG8_LDA(At, 0, 1); PG8_STAGE(PG8_SB(0, 0), b2, voffB); PG8_STAGE(PG8_SB(0, 1), b2 + hstepB, voffB); PG8_STAGE(PG8_SA(0, 0), a2, voffA);
;             PG8_WAIT_V(8); PG8_WAIT_L(0); PG8_BAR; PG8_MMA(1, 0, At, B0); PG8_MMA(1, 1, At, B1); PG8_BAR; PG8_SCHED;
;             PG8_LDB(B0, 1, 0); PG8_LDB(B1, 1, 1); PG8_SCHED; PG8_LDA(At, 1, 0); PG8_STAGE(PG8_SA(0, 1), a2 + hstepA, voffA);
;             PG8_WAIT_V(8); PG8_WAIT_L(0); PG8_BAR; PG8_MMA(0, 0, At, B0); PG8_MMA(0, 1, At, B1); PG8_BAR; PG8_SCHED;
;             PG8_LDA(At, 1, 1); PG8_STAGE(PG8_SB(1, 0), b3, voffB); PG8_STAGE(PG8_SB(1, 1), b3 + hstepB, voffB); PG8_STAGE(PG8_SA(1, 0), a3, voffA);
;             PG8_WAIT_V(8); PG8_WAIT_L(0); PG8_BAR; PG8_MMA(1, 0, At, B0); PG8_MMA(1, 1, At, B1); PG8_BAR; PG8_SCHED;
.LBB0_471:
	s_add_u32 s12, s10, 0xfffc0080
	s_addc_u32 s13, s11, -1
	s_add_i32 s83, 0, 0x10000
	s_cmp_eq_u32 s82, 12
	s_cselect_b32 s15, s9, s13
	s_cselect_b32 s14, s45, s12
	s_cselect_b32 s13, s43, s62
	s_cselect_b32 s12, s48, s49
	s_add_i32 vcc_lo, 0, 0x14000
	v_add_u32_e32 v154, s83, v165
	v_add_u32_e32 v162, vcc_lo, v165
	ds_read_b128 v[50:53], v154
	ds_read_b128 v[102:105], v154 offset:1024
	ds_read_b128 v[150:153], v154 offset:2048
	ds_read_b128 v[154:157], v154 offset:3072
	ds_read_b128 v[158:161], v162
	ds_read_b128 v[180:183], v162 offset:1024
	ds_read_b128 v[184:187], v162 offset:2048
	ds_read_b128 v[188:191], v162 offset:3072
	v_lshl_add_u64 v[162:163], s[10:11], 0, v[148:149]
	s_add_i32 m0, s41, 0xc000
	ds_read_b128 v[192:195], v166
	ds_read_b128 v[196:199], v166 offset:1024
	ds_read_b128 v[200:203], v166 offset:2048
	ds_read_b128 v[204:207], v166 offset:3072
	ds_read_b128 v[208:211], v166 offset:4096
	ds_read_b128 v[212:215], v166 offset:5120
	ds_read_b128 v[216:219], v166 offset:6144
	ds_read_b128 v[220:223], v166 offset:7168
	global_load_lds_dwordx4 v[162:163], off
	v_lshl_add_u64 v[162:163], s[10:11], 0, v[146:147]
	s_add_i32 m0, s41, 0xe000
	s_nop 0
	global_load_lds_dwordx4 v[162:163], off
	s_waitcnt vmcnt(8)
	s_waitcnt lgkmcnt(0)
	s_setprio 1
	s_barrier
	v_mfma_f32_16x16x32_bf16 v[130:133], v[50:53], v[192:195], v[130:133]
	v_mfma_f32_16x16x32_bf16 v[126:129], v[150:153], v[192:195], v[126:129]
	v_mfma_f32_16x16x32_bf16 v[114:117], v[50:53], v[200:203], v[114:117]
	v_mfma_f32_16x16x32_bf16 v[110:113], v[150:153], v[200:203], v[110:113]
	v_mfma_f32_16x16x32_bf16 v[94:97], v[50:53], v[208:211], v[94:97]
	v_mfma_f32_16x16x32_bf16 v[90:93], v[150:153], v[208:211], v[90:93]
	v_mfma_f32_16x16x32_bf16 v[78:81], v[50:53], v[216:219], v[78:81]
	v_mfma_f32_16x16x32_bf16 v[74:77], v[150:153], v[216:219], v[74:77]
	v_mfma_f32_16x16x32_bf16 v[130:133], v[102:105], v[196:199], v[130:133]
	v_mfma_f32_16x16x32_bf16 v[126:129], v[154:157], v[196:199], v[126:129]
	v_mfma_f32_16x16x32_bf16 v[114:117], v[102:105], v[204:207], v[114:117]
	v_mfma_f32_16x16x32_bf16 v[110:113], v[154:157], v[204:207], v[110:113]
	v_mfma_f32_16x16x32_bf16 v[94:97], v[102:105], v[212:215], v[94:97]
	v_mfma_f32_16x16x32_bf16 v[90:93], v[154:157], v[212:215], v[90:93]
	v_mfma_f32_16x16x32_bf16 v[78:81], v[102:105], v[220:223], v[78:81]
	v_mfma_f32_16x16x32_bf16 v[74:77], v[154:157], v[220:223], v[74:77]
	v_mfma_f32_16x16x32_bf16 v[134:137], v[158:161], v[192:195], v[134:137]
	v_mfma_f32_16x16x32_bf16 v[122:125], v[184:187], v[192:195], v[122:125]
	v_mfma_f32_16x16x32_bf16 v[118:121], v[158:161], v[200:203], v[118:121]
	v_mfma_f32_16x16x32_bf16 v[106:109], v[184:187], v[200:203], v[106:109]
	v_mfma_f32_16x16x32_bf16 v[98:101], v[158:161], v[208:211], v[98:101]
	v_mfma_f32_16x16x32_bf16 v[86:89], v[184:187], v[208:211], v[86:89]
	v_mfma_f32_16x16x32_bf16 v[82:85], v[158:161], v[216:219], v[82:85]
	v_mfma_f32_16x16x32_bf16 v[70:73], v[184:187], v[216:219], v[70:73]
	v_mfma_f32_16x16x32_bf16 v[134:137], v[180:183], v[196:199], v[134:137]
	v_mfma_f32_16x16x32_bf16 v[122:125], v[188:191], v[196:199], v[122:125]
	v_mfma_f32_16x16x32_bf16 v[118:121], v[180:183], v[204:207], v[118:121]
	v_mfma_f32_16x16x32_bf16 v[106:109], v[188:191], v[204:207], v[106:109]
	v_mfma_f32_16x16x32_bf16 v[98:101], v[180:183], v[212:215], v[98:101]
	v_mfma_f32_16x16x32_bf16 v[86:89], v[188:191], v[212:215], v[86:89]
	v_mfma_f32_16x16x32_bf16 v[82:85], v[180:183], v[220:223], v[82:85]
	v_mfma_f32_16x16x32_bf16 v[70:73], v[188:191], v[220:223], v[70:73]
	s_barrier
	s_setprio 0
	s_add_i32 s83, s83, s37
	v_lshl_add_u64 v[162:163], s[12:13], 0, v[140:141]
	s_mov_b32 m0, s83
	ds_read_b128 v[192:195], v166 offset:16384
	ds_read_b128 v[196:199], v166 offset:17408
	ds_read_b128 v[200:203], v166 offset:18432
	ds_read_b128 v[204:207], v166 offset:19456
	ds_read_b128 v[208:211], v166 offset:20480
	ds_read_b128 v[212:215], v166 offset:21504
	ds_read_b128 v[216:219], v166 offset:22528
	ds_read_b128 v[220:223], v166 offset:23552
	global_load_lds_dwordx4 v[162:163], off
	s_add_i32 m0, s83, 0x2000
	s_add_u32 s84, s12, 0x40000
	v_lshl_add_u64 v[224:225], s[12:13], 0, v[144:145]
	s_addc_u32 s85, s13, 0
	s_add_i32 s83, vcc_lo, s37
	global_load_lds_dwordx4 v[224:225], off
	v_lshl_add_u64 v[226:227], s[84:85], 0, v[140:141]
	s_mov_b32 m0, s83
	v_lshl_add_u64 v[228:229], s[14:15], 0, v[142:143]
	global_load_lds_dwordx4 v[226:227], off
	v_lshl_add_u64 v[226:227], s[84:85], 0, v[144:145]
	s_add_i32 m0, s83, 0x2000
	s_nop 0
	global_load_lds_dwordx4 v[226:227], off
	v_lshl_add_u64 v[226:227], s[14:15], 0, v[138:139]
	s_mov_b32 m0, s41
	s_nop 0
	global_load_lds_dwordx4 v[226:227], off
	s_mov_b32 m0, s90
	s_nop 0
	global_load_lds_dwordx4 v[228:229], off
	s_waitcnt vmcnt(8)
	s_waitcnt lgkmcnt(0)
	s_setprio 1
	s_barrier
; #define PG8_STAGE(bufoff, gbase, voff) do { _Pragma("unroll") for (int _i = 0; _i < 2; ++_i) \
;         __builtin_amdgcn_global_load_lds((const unsigned*)((const char*)(gbase) + (voff)[_i]), (LAS unsigned*)(lds + (bufoff) + ldsw + _i * 8192), 16, 0, 0); } while (0)
; #define PG8_LDA(dst, b, h) do { _Pragma("unroll") for (int m = 0; m < 4; ++m) _Pragma("unroll") for (int k = 0; k < 2; ++k) dst[m][k] = *(const LAS bf16x8*)(lds + PG8_SA(b, h) + aoff + m * 2048 + k * 1024); } while (0)
; #define PG8_LDB(dst, b, h) do { _Pragma("unroll") for (int n = 0; n < 2; ++n) _Pragma("unroll") for (int k = 0; k < 2; ++k) dst[n][k] = *(const LAS bf16x8*)(lds + PG8_SB(b, h) + boff + n * 2048 + k * 1024); } while (0)
; #define PG8_MMA(ai, bj, At, Bt) do { __builtin_amdgcn_s_setprio(1); _Pragma("unroll") for (int m = 0; m < 4; ++m) _Pragma("unroll") for (int n = 0; n < 2; ++n) _Pragma("unroll") for (int k = 0; k < 2; ++k) \
;         acc[ai][bj][m][n] = __builtin_amdgcn_mfma_f32_16x16x32_bf16(Bt[n][k], At[m][k], acc[ai][bj][m][n], 0, 0, 0); __builtin_amdgcn_s_setprio(0); } while (0)
; #define PG8_WAIT_V(n) asm volatile("s_waitcnt vmcnt(" #n ")" ::: "memory")
; #define PG8_WAIT_L(n) asm volatile("s_waitcnt lgkmcnt(" #n ")" ::: "memory")
; #define PG8_BAR __builtin_amdgcn_s_barrier()
; #define PG8_SCHED __builtin_amdgcn_sched_barrier(0)
; template <class Epi, class Sched>
; __device__ __forceinline__ void gemm_phase(LAS unsigned char* lds, const Gemm g, const Sched S, const Epi E, const int tid) {
;     ...
;             PG8_WAIT_V(8); PG8_WAIT_L(0); PG8_BAR; PG8_MMA(0, 0, At, B0); PG8_MMA(0, 1, At, B1); PG8_BAR; PG8_SCHED;
;             PG8_LDA(At, 0, 1); PG8_STAGE(PG8_SB(0, 0), b2, voffB); PG8_STAGE(PG8_SB(0, 1), b2 + hstepB, voffB); PG8_STAGE(PG8_SA(0, 0), a2, voffA);
;             PG8_WAIT_V(8); PG8_WAIT_L(0); PG8_BAR; PG8_MMA(1, 0, At, B0); PG8_MMA(1, 1, At, B1); PG8_BAR; PG8_SCHED;
;             PG8_LDB(B0, 1, 0); PG8_LDB(B1, 1, 1); PG8_SCHED; PG8_LDA(At, 1, 0); PG8_STAGE(PG8_SA(0, 1), a2 + hstepA, voffA);
;             PG8_WAIT_V(8); PG8_WAIT_L(0); PG8_BAR; PG8_MMA(0, 0, At, B0); PG8_MMA(0, 1, At, B1); PG8_BAR; PG8_SCHED;
	v_mfma_f32_16x16x32_bf16 v[62:65], v[50:53], v[192:195], v[62:65]
	v_mfma_f32_16x16x32_bf16 v[58:61], v[150:153], v[192:195], v[58:61]
	v_mfma_f32_16x16x32_bf16 v[42:45], v[50:53], v[200:203], v[42:45]
	v_mfma_f32_16x16x32_bf16 v[38:41], v[150:153], v[200:203], v[38:41]
	v_mfma_f32_16x16x32_bf16 v[26:29], v[50:53], v[208:211], v[26:29]
	v_mfma_f32_16x16x32_bf16 v[22:25], v[150:153], v[208:211], v[22:25]
	v_mfma_f32_16x16x32_bf16 v[10:13], v[50:53], v[216:219], v[10:13]
	v_mfma_f32_16x16x32_bf16 v[6:9], v[150:153], v[216:219], v[6:9]
	v_mfma_f32_16x16x32_bf16 v[62:65], v[102:105], v[196:199], v[62:65]
	v_mfma_f32_16x16x32_bf16 v[58:61], v[154:157], v[196:199], v[58:61]
	v_mfma_f32_16x16x32_bf16 v[42:45], v[102:105], v[204:207], v[42:45]
	v_mfma_f32_16x16x32_bf16 v[38:41], v[154:157], v[204:207], v[38:41]
	v_mfma_f32_16x16x32_bf16 v[26:29], v[102:105], v[212:215], v[26:29]
	v_mfma_f32_16x16x32_bf16 v[22:25], v[154:157], v[212:215], v[22:25]
	v_mfma_f32_16x16x32_bf16 v[10:13], v[102:105], v[220:223], v[10:13]
	v_mfma_f32_16x16x32_bf16 v[6:9], v[154:157], v[220:223], v[6:9]
	v_mfma_f32_16x16x32_bf16 v[54:57], v[184:187], v[192:195], v[54:57]
	v_mfma_f32_16x16x32_bf16 v[46:49], v[158:161], v[200:203], v[46:49]
	v_mfma_f32_16x16x32_bf16 v[34:37], v[184:187], v[200:203], v[34:37]
	v_mfma_f32_16x16x32_bf16 v[30:33], v[158:161], v[208:211], v[30:33]
	v_mfma_f32_16x16x32_bf16 v[18:21], v[184:187], v[208:211], v[18:21]
	v_mfma_f32_16x16x32_bf16 v[14:17], v[158:161], v[216:219], v[14:17]
	v_mfma_f32_16x16x32_bf16 v[2:5], v[184:187], v[216:219], v[2:5]
	v_mfma_f32_16x16x32_bf16 v[50:53], v[158:161], v[192:195], v[66:69]
	v_mfma_f32_16x16x32_bf16 v[54:57], v[188:191], v[196:199], v[54:57]
	v_mfma_f32_16x16x32_bf16 v[46:49], v[180:183], v[204:207], v[46:49]
	v_mfma_f32_16x16x32_bf16 v[34:37], v[188:191], v[204:207], v[34:37]
	v_mfma_f32_16x16x32_bf16 v[30:33], v[180:183], v[212:215], v[30:33]
	v_mfma_f32_16x16x32_bf16 v[18:21], v[188:191], v[212:215], v[18:21]
	v_mfma_f32_16x16x32_bf16 v[14:17], v[180:183], v[220:223], v[14:17]
	v_mfma_f32_16x16x32_bf16 v[2:5], v[188:191], v[220:223], v[2:5]
	v_mfma_f32_16x16x32_bf16 v[50:53], v[180:183], v[196:199], v[50:53]
	s_barrier
	s_setprio 0
	s_add_i32 s83, 0, 0x18000
	s_add_i32 s84, 0, 0x1c000
	v_add_u32_e32 v154, s83, v165
	v_add_u32_e32 v167, s84, v165
	ds_read_b128 v[66:69], v154
	ds_read_b128 v[102:105], v154 offset:1024
	ds_read_b128 v[150:153], v154 offset:2048
	ds_read_b128 v[154:157], v154 offset:3072
	ds_read_b128 v[158:161], v167
	ds_read_b128 v[180:183], v167 offset:1024
	ds_read_b128 v[184:187], v167 offset:2048
	ds_read_b128 v[188:191], v167 offset:3072
	s_add_u32 s14, s14, 0x40000
	s_addc_u32 s15, s15, 0
	s_mov_b32 m0, s91
	v_lshl_add_u64 v[230:231], s[14:15], 0, v[138:139]
	ds_read_b128 v[192:195], v166 offset:32768
	ds_read_b128 v[196:199], v166 offset:33792
	ds_read_b128 v[200:203], v166 offset:34816
	ds_read_b128 v[204:207], v166 offset:35840
	ds_read_b128 v[208:211], v166 offset:36864
	ds_read_b128 v[212:215], v166 offset:37888
	ds_read_b128 v[216:219], v166 offset:38912
	ds_read_b128 v[220:223], v166 offset:39936
	global_load_lds_dwordx4 v[230:231], off
	v_lshl_add_u64 v[230:231], s[14:15], 0, v[142:143]
	s_mov_b32 m0, s68
	s_nop 0
	global_load_lds_dwordx4 v[230:231], off
	s_waitcnt vmcnt(8)
	s_waitcnt lgkmcnt(0)
	s_setprio 1
	s_barrier
	v_mfma_f32_16x16x32_bf16 v[130:133], v[66:69], v[192:195], v[130:133]
	v_mfma_f32_16x16x32_bf16 v[126:129], v[150:153], v[192:195], v[126:129]
	v_mfma_f32_16x16x32_bf16 v[114:117], v[66:69], v[200:203], v[114:117]
	v_mfma_f32_16x16x32_bf16 v[110:113], v[150:153], v[200:203], v[110:113]
	v_mfma_f32_16x16x32_bf16 v[94:97], v[66:69], v[208:211], v[94:97]
	v_mfma_f32_16x16x32_bf16 v[90:93], v[150:153], v[208:211], v[90:93]
	v_mfma_f32_16x16x32_bf16 v[78:81], v[66:69], v[216:219], v[78:81]
	v_mfma_f32_16x16x32_bf16 v[74:77], v[150:153], v[216:219], v[74:77]
	v_mfma_f32_16x16x32_bf16 v[130:133], v[102:105], v[196:199], v[130:133]
	v_mfma_f32_16x16x32_bf16 v[126:129], v[154:157], v[196:199], v[126:129]
	v_mfma_f32_16x16x32_bf16 v[114:117], v[102:105], v[204:207], v[114:117]
	v_mfma_f32_16x16x32_bf16 v[110:113], v[154:157], v[204:207], v[110:113]
	v_mfma_f32_16x16x32_bf16 v[94:97], v[102:105], v[212:215], v[94:97]
	v_mfma_f32_16x16x32_bf16 v[90:93], v[154:157], v[212:215], v[90:93]
	v_mfma_f32_16x16x32_bf16 v[78:81], v[102:105], v[220:223], v[78:81]
	v_mfma_f32_16x16x32_bf16 v[74:77], v[154:157], v[220:223], v[74:77]
	v_mfma_f32_16x16x32_bf16 v[134:137], v[158:161], v[192:195], v[134:137]
	v_mfma_f32_16x16x32_bf16 v[122:125], v[184:187], v[192:195], v[122:125]
	v_mfma_f32_16x16x32_bf16 v[118:121], v[158:161], v[200:203], v[118:121]
	v_mfma_f32_16x16x32_bf16 v[106:109], v[184:187], v[200:203], v[106:109]
	v_mfma_f32_16x16x32_bf16 v[98:101], v[158:161], v[208:211], v[98:101]
	v_mfma_f32_16x16x32_bf16 v[86:89], v[184:187], v[208:211], v[86:89]
	v_mfma_f32_16x16x32_bf16 v[82:85], v[158:161], v[216:219], v[82:85]
	v_mfma_f32_16x16x32_bf16 v[70:73], v[184:187], v[216:219], v[70:73]
	v_mfma_f32_16x16x32_bf16 v[134:137], v[180:183], v[196:199], v[134:137]
	v_mfma_f32_16x16x32_bf16 v[122:125], v[188:191], v[196:199], v[122:125]
	v_mfma_f32_16x16x32_bf16 v[118:121], v[180:183], v[204:207], v[118:121]
	v_mfma_f32_16x16x32_bf16 v[106:109], v[188:191], v[204:207], v[106:109]
	v_mfma_f32_16x16x32_bf16 v[98:101], v[180:183], v[212:215], v[98:101]
	v_mfma_f32_16x16x32_bf16 v[86:89], v[188:191], v[212:215], v[86:89]
	v_mfma_f32_16x16x32_bf16 v[82:85], v[180:183], v[220:223], v[82:85]
	v_mfma_f32_16x16x32_bf16 v[70:73], v[188:191], v[220:223], v[70:73]
	s_barrier
; #define PG8_STAGE(bufoff, gbase, voff) do { _Pragma("unroll") for (int _i = 0; _i < 2; ++_i) \
;         __builtin_amdgcn_global_load_lds((const unsigned*)((const char*)(gbase) + (voff)[_i]), (LAS unsigned*)(lds + (bufoff) + ldsw + _i * 8192), 16, 0, 0); } while (0)
; #define PG8_LDA(dst, b, h) do { _Pragma("unroll") for (int m = 0; m < 4; ++m) _Pragma("unroll") for (int k = 0; k < 2; ++k) dst[m][k] = *(const LAS bf16x8*)(lds + PG8_SA(b, h) + aoff + m * 2048 + k * 1024); } while (0)
; #define PG8_MMA(ai, bj, At, Bt) do { __builtin_amdgcn_s_setprio(1); _Pragma("unroll") for (int m = 0; m < 4; ++m) _Pragma("unroll") for (int n = 0; n < 2; ++n) _Pragma("unroll") for (int k = 0; k < 2; ++k) \
;         acc[ai][bj][m][n] = __builtin_amdgcn_mfma_f32_16x16x32_bf16(Bt[n][k], At[m][k], acc[ai][bj][m][n], 0, 0, 0); __builtin_amdgcn_s_setprio(0); } while (0)
; #define PG8_WAIT_V(n) asm volatile("s_waitcnt vmcnt(" #n ")" ::: "memory")
; #define PG8_WAIT_L(n) asm volatile("s_waitcnt lgkmcnt(" #n ")" ::: "memory")
; #define PG8_BAR __builtin_amdgcn_s_barrier()
; #define PG8_SCHED __builtin_amdgcn_sched_barrier(0)
; template <class Epi, class Sched>
; __device__ __forceinline__ void gemm_phase(LAS unsigned char* lds, const Gemm g, const Sched S, const Epi E, const int tid) {
;     ...
;             PG8_LDA(At, 1, 1); PG8_STAGE(PG8_SB(1, 0), b3, voffB); PG8_STAGE(PG8_SB(1, 1), b3 + hstepB, voffB); PG8_STAGE(PG8_SA(1, 0), a3, voffA);
;             PG8_WAIT_V(8); PG8_WAIT_L(0); PG8_BAR; PG8_MMA(1, 0, At, B0); PG8_MMA(1, 1, At, B1); PG8_BAR; PG8_SCHED;
;         }
;         if (wr == 0) PG8_BAR;
	s_setprio 0
	s_add_i32 s14, s83, s37
	v_lshl_add_u64 v[162:163], v[162:163], 0, s[64:65]
	s_mov_b32 m0, s14
	ds_read_b128 v[192:195], v166 offset:49152
	ds_read_b128 v[196:199], v166 offset:50176
	ds_read_b128 v[200:203], v166 offset:51200
	ds_read_b128 v[204:207], v166 offset:52224
	ds_read_b128 v[208:211], v166 offset:53248
	ds_read_b128 v[212:215], v166 offset:54272
	ds_read_b128 v[216:219], v166 offset:55296
	ds_read_b128 v[220:223], v166 offset:56320
	global_load_lds_dwordx4 v[162:163], off
	s_add_i32 m0, s14, 0x2000
	s_add_u32 s12, s12, 0x40080
	v_lshl_add_u64 v[162:163], v[224:225], 0, s[64:65]
	s_addc_u32 s13, s13, 0
	s_add_i32 s14, s84, s37
	global_load_lds_dwordx4 v[162:163], off
	v_lshl_add_u64 v[162:163], s[12:13], 0, v[140:141]
	s_mov_b32 m0, s14
	s_nop 0
	global_load_lds_dwordx4 v[162:163], off
	v_lshl_add_u64 v[162:163], s[12:13], 0, v[144:145]
	s_add_i32 m0, s14, 0x2000
	s_nop 0
	global_load_lds_dwordx4 v[162:163], off
	v_lshl_add_u64 v[162:163], v[226:227], 0, s[64:65]
	s_mov_b32 m0, s29
	s_nop 0
	global_load_lds_dwordx4 v[162:163], off
	v_lshl_add_u64 v[162:163], v[228:229], 0, s[64:65]
	s_mov_b32 m0, s92
	s_nop 0
	global_load_lds_dwordx4 v[162:163], off
	s_waitcnt vmcnt(8)
	s_waitcnt lgkmcnt(0)
	s_setprio 1
	s_barrier
	v_mfma_f32_16x16x32_bf16 v[62:65], v[66:69], v[192:195], v[62:65]
	v_mfma_f32_16x16x32_bf16 v[58:61], v[150:153], v[192:195], v[58:61]
	v_mfma_f32_16x16x32_bf16 v[42:45], v[66:69], v[200:203], v[42:45]
	v_mfma_f32_16x16x32_bf16 v[38:41], v[150:153], v[200:203], v[38:41]
	v_mfma_f32_16x16x32_bf16 v[26:29], v[66:69], v[208:211], v[26:29]
	v_mfma_f32_16x16x32_bf16 v[22:25], v[150:153], v[208:211], v[22:25]
	v_mfma_f32_16x16x32_bf16 v[10:13], v[66:69], v[216:219], v[10:13]
	v_mfma_f32_16x16x32_bf16 v[6:9], v[150:153], v[216:219], v[6:9]
	v_mfma_f32_16x16x32_bf16 v[62:65], v[102:105], v[196:199], v[62:65]
	v_mfma_f32_16x16x32_bf16 v[58:61], v[154:157], v[196:199], v[58:61]
	v_mfma_f32_16x16x32_bf16 v[42:45], v[102:105], v[204:207], v[42:45]
	v_mfma_f32_16x16x32_bf16 v[38:41], v[154:157], v[204:207], v[38:41]
	v_mfma_f32_16x16x32_bf16 v[26:29], v[102:105], v[212:215], v[26:29]
	v_mfma_f32_16x16x32_bf16 v[22:25], v[154:157], v[212:215], v[22:25]
	v_mfma_f32_16x16x32_bf16 v[10:13], v[102:105], v[220:223], v[10:13]
	v_mfma_f32_16x16x32_bf16 v[6:9], v[154:157], v[220:223], v[6:9]
	v_mfma_f32_16x16x32_bf16 v[50:53], v[158:161], v[192:195], v[50:53]
	v_mfma_f32_16x16x32_bf16 v[66:69], v[180:183], v[196:199], v[50:53]
	v_mfma_f32_16x16x32_bf16 v[50:53], v[184:187], v[192:195], v[54:57]
	v_mfma_f32_16x16x32_bf16 v[46:49], v[158:161], v[200:203], v[46:49]
	v_mfma_f32_16x16x32_bf16 v[34:37], v[184:187], v[200:203], v[34:37]
	v_mfma_f32_16x16x32_bf16 v[30:33], v[158:161], v[208:211], v[30:33]
	v_mfma_f32_16x16x32_bf16 v[18:21], v[184:187], v[208:211], v[18:21]
	v_mfma_f32_16x16x32_bf16 v[14:17], v[158:161], v[216:219], v[14:17]
	v_mfma_f32_16x16x32_bf16 v[2:5], v[184:187], v[216:219], v[2:5]
	v_mfma_f32_16x16x32_bf16 v[54:57], v[188:191], v[196:199], v[50:53]
	v_mfma_f32_16x16x32_bf16 v[46:49], v[180:183], v[204:207], v[46:49]
	v_mfma_f32_16x16x32_bf16 v[34:37], v[188:191], v[204:207], v[34:37]
	v_mfma_f32_16x16x32_bf16 v[30:33], v[180:183], v[212:215], v[30:33]
	v_mfma_f32_16x16x32_bf16 v[18:21], v[188:191], v[212:215], v[18:21]
	v_mfma_f32_16x16x32_bf16 v[14:17], v[180:183], v[220:223], v[14:17]
	v_mfma_f32_16x16x32_bf16 v[2:5], v[188:191], v[220:223], v[2:5]
	s_barrier
	s_setprio 0
	s_add_i32 s82, s82, 2
	s_add_u32 s49, s49, 0x100
	s_addc_u32 s62, s62, 0
	s_add_u32 s10, s10, 0x100
	s_addc_u32 s11, s11, 0
	s_cmp_gt_u32 s82, 13
	s_cbranch_scc0 .LBB0_471
	s_and_b64 vcc, exec, s[18:19]
	s_cbranch_vccz .LBB0_474
	s_barrier

; #define PG8_STAGE(bufoff, gbase, voff) do { _Pragma("unroll") for (int _i = 0; _i < 2; ++_i) \
;         __builtin_amdgcn_global_load_lds((const unsigned*)((const char*)(gbase) + (voff)[_i]), (LAS unsigned*)(lds + (bufoff) + ldsw + _i * 8192), 16, 0, 0); } while (0)
; #define PG8_LDA(dst, b, h) do { _Pragma("unroll") for (int m = 0; m < 4; ++m) _Pragma("unroll") for (int k = 0; k < 2; ++k) dst[m][k] = *(const LAS bf16x8*)(lds + PG8_SA(b, h) + aoff + m * 2048 + k * 1024); } while (0)
; #define PG8_LDB(dst, b, h) do { _Pragma("unroll") for (int n = 0; n < 2; ++n) _Pragma("unroll") for (int k = 0; k < 2; ++k) dst[n][k] = *(const LAS bf16x8*)(lds + PG8_SB(b, h) + boff + n * 2048 + k * 1024); } while (0)
; #define PG8_WAIT_V(n) asm volatile("s_waitcnt vmcnt(" #n ")" ::: "memory")
; #define PG8_BAR __builtin_amdgcn_s_barrier()
; template <class Epi, class Sched>
; __device__ __forceinline__ void gemm_phase(LAS unsigned char* lds, const Gemm g, const Sched S, const Epi E, const int tid) {
;     ...
;         for (int t = 0; t < nt; t += 2) {
;             const bool last = (t == nt - 2);
;             const char* a1 = cA + (size_t)(t + 1) * kstep;
;             const char* a2 = last ? nA : cA + (size_t)(t + 2) * kstep; const char* b2 = last ? nB : cB + (size_t)(t + 2) * kstep;
;             const char* a3 = a2 + kstep; const char* b3 = b2 + kstep;
;             PG8_LDB(B0, 0, 0); PG8_LDB(B1, 0, 1); PG8_SCHED; PG8_LDA(At, 0, 0); PG8_STAGE(PG8_SA(1, 1), a1 + hstepA, voffA);
;             PG8_WAIT_V(8); PG8_WAIT_L(0); PG8_BAR; PG8_MMA(0, 0, At, B0); PG8_MMA(0, 1, At, B1); PG8_BAR; PG8_SCHED;
;             PG8_LDA(At, 0, 1); PG8_STAGE(PG8_SB(0, 0), b2, voffB); PG8_STAGE(PG8_SB(0, 1), b2 + hstepB, voffB); PG8_STAGE(PG8_SA(0, 0), a2, voffA);
;             PG8_WAIT_V(8); PG8_WAIT_L(0); PG8_BAR; PG8_MMA(1, 0, At, B0); PG8_MMA(1, 1, At, B1); PG8_BAR; PG8_SCHED;
;             PG8_LDB(B0, 1, 0); PG8_LDB(B1, 1, 1); PG8_SCHED; PG8_LDA(At, 1, 0); PG8_STAGE(PG8_SA(0, 1), a2 + hstepA, voffA);
;             PG8_WAIT_V(8); PG8_WAIT_L(0); PG8_BAR; PG8_MMA(0, 0, At, B0); PG8_MMA(0, 1, At, B1); PG8_BAR; PG8_SCHED;
;             PG8_LDA(At, 1, 1); PG8_STAGE(PG8_SB(1, 0), b3, voffB); PG8_STAGE(PG8_SB(1, 1), b3 + hstepB, voffB); PG8_STAGE(PG8_SA(1, 0), a3, voffA);
;             PG8_WAIT_V(8); PG8_WAIT_L(0); PG8_BAR; PG8_MMA(1, 0, At, B0); PG8_MMA(1, 1, At, B1); PG8_BAR; PG8_SCHED;
.LBB0_778:
	s_add_i32 s94, s20, 2
	s_add_u32 s95, s18, 0x80
	s_addc_u32 s21, s19, 0
	s_add_i32 vcc_lo, 0, 0x10000
	s_cmp_eq_u32 s69, s20
	s_cselect_b32 s21, s9, s21
	s_cselect_b32 s20, s8, s95
	s_cselect_b32 s97, s17, s93
	s_cselect_b32 s96, s16, s92
	s_add_i32 s95, 0, 0x14000
	v_add_u32_e32 v142, vcc_lo, v198
	v_add_u32_e32 v167, s95, v198
	ds_read_b128 v[126:129], v142
	ds_read_b128 v[134:137], v142 offset:1024
	ds_read_b128 v[138:141], v142 offset:2048
	ds_read_b128 v[142:145], v142 offset:3072
	ds_read_b128 v[146:149], v167
	ds_read_b128 v[150:153], v167 offset:1024
	ds_read_b128 v[154:157], v167 offset:2048
	ds_read_b128 v[186:189], v167 offset:3072
	v_lshl_add_u64 v[224:225], s[18:19], 0, v[184:185]
	s_add_i32 m0, s37, 0xc000
	ds_read_b128 v[190:193], v199
	ds_read_b128 v[194:197], v199 offset:1024
	ds_read_b128 v[200:203], v199 offset:2048
	ds_read_b128 v[204:207], v199 offset:3072
	ds_read_b128 v[208:211], v199 offset:4096
	ds_read_b128 v[212:215], v199 offset:5120
	ds_read_b128 v[216:219], v199 offset:6144
	ds_read_b128 v[220:223], v199 offset:7168
	global_load_lds_dwordx4 v[224:225], off
	v_lshl_add_u64 v[224:225], s[18:19], 0, v[182:183]
	s_add_i32 m0, s37, 0xe000
	s_nop 0
	global_load_lds_dwordx4 v[224:225], off
	s_waitcnt vmcnt(8)
	s_waitcnt lgkmcnt(0)
	s_setprio 1
	s_barrier
	v_mfma_f32_16x16x32_bf16 v[130:133], v[126:129], v[190:193], v[130:133]
	v_mfma_f32_16x16x32_bf16 v[122:125], v[138:141], v[190:193], v[122:125]
	v_mfma_f32_16x16x32_bf16 v[110:113], v[126:129], v[200:203], v[110:113]
	v_mfma_f32_16x16x32_bf16 v[106:109], v[138:141], v[200:203], v[106:109]
	v_mfma_f32_16x16x32_bf16 v[94:97], v[126:129], v[208:211], v[94:97]
	v_mfma_f32_16x16x32_bf16 v[90:93], v[138:141], v[208:211], v[90:93]
	v_mfma_f32_16x16x32_bf16 v[78:81], v[126:129], v[216:219], v[78:81]
	v_mfma_f32_16x16x32_bf16 v[74:77], v[138:141], v[216:219], v[74:77]
	v_mfma_f32_16x16x32_bf16 v[130:133], v[134:137], v[194:197], v[130:133]
	v_mfma_f32_16x16x32_bf16 v[122:125], v[142:145], v[194:197], v[122:125]
	v_mfma_f32_16x16x32_bf16 v[110:113], v[134:137], v[204:207], v[110:113]
	v_mfma_f32_16x16x32_bf16 v[106:109], v[142:145], v[204:207], v[106:109]
	v_mfma_f32_16x16x32_bf16 v[94:97], v[134:137], v[212:215], v[94:97]
	v_mfma_f32_16x16x32_bf16 v[90:93], v[142:145], v[212:215], v[90:93]
	v_mfma_f32_16x16x32_bf16 v[78:81], v[134:137], v[220:223], v[78:81]
	v_mfma_f32_16x16x32_bf16 v[74:77], v[142:145], v[220:223], v[74:77]
	v_mfma_f32_16x16x32_bf16 v[118:121], v[146:149], v[190:193], v[118:121]
	v_mfma_f32_16x16x32_bf16 v[114:117], v[154:157], v[190:193], v[114:117]
	v_mfma_f32_16x16x32_bf16 v[102:105], v[146:149], v[200:203], v[102:105]
	v_mfma_f32_16x16x32_bf16 v[98:101], v[154:157], v[200:203], v[98:101]
	v_mfma_f32_16x16x32_bf16 v[86:89], v[146:149], v[208:211], v[86:89]
	v_mfma_f32_16x16x32_bf16 v[82:85], v[154:157], v[208:211], v[82:85]
	v_mfma_f32_16x16x32_bf16 v[70:73], v[146:149], v[216:219], v[70:73]
	v_mfma_f32_16x16x32_bf16 v[66:69], v[154:157], v[216:219], v[66:69]
	v_mfma_f32_16x16x32_bf16 v[118:121], v[150:153], v[194:197], v[118:121]
	v_mfma_f32_16x16x32_bf16 v[114:117], v[186:189], v[194:197], v[114:117]
	v_mfma_f32_16x16x32_bf16 v[102:105], v[150:153], v[204:207], v[102:105]
	v_mfma_f32_16x16x32_bf16 v[98:101], v[186:189], v[204:207], v[98:101]
	v_mfma_f32_16x16x32_bf16 v[86:89], v[150:153], v[212:215], v[86:89]
	v_mfma_f32_16x16x32_bf16 v[82:85], v[186:189], v[212:215], v[82:85]
	v_mfma_f32_16x16x32_bf16 v[70:73], v[150:153], v[220:223], v[70:73]
	v_mfma_f32_16x16x32_bf16 v[66:69], v[186:189], v[220:223], v[66:69]
	s_barrier
	s_setprio 0
	s_add_i32 vcc_lo, vcc_lo, s29
	v_lshl_add_u64 v[224:225], s[96:97], 0, v[160:161]
	s_mov_b32 m0, vcc_lo
	ds_read_b128 v[190:193], v199 offset:16384
	ds_read_b128 v[194:197], v199 offset:17408
	ds_read_b128 v[200:203], v199 offset:18432
	ds_read_b128 v[204:207], v199 offset:19456
	ds_read_b128 v[208:211], v199 offset:20480
	ds_read_b128 v[212:215], v199 offset:21504
	ds_read_b128 v[216:219], v199 offset:22528
	ds_read_b128 v[220:223], v199 offset:23552
	global_load_lds_dwordx4 v[224:225], off
	s_add_i32 m0, vcc_lo, 0x2000
	v_lshl_add_u64 v[226:227], s[96:97], 0, v[164:165]
	s_add_u32 s96, s96, s62
	s_addc_u32 s97, s97, 0
	s_add_i32 s95, s95, s29
	global_load_lds_dwordx4 v[226:227], off
	v_lshl_add_u64 v[228:229], s[96:97], 0, v[160:161]
	s_mov_b32 m0, s95
	v_lshl_add_u64 v[230:231], s[96:97], 0, v[164:165]
	global_load_lds_dwordx4 v[228:229], off
	s_add_i32 m0, s95, 0x2000
	v_lshl_add_u64 v[232:233], s[20:21], 0, v[158:159]
	global_load_lds_dwordx4 v[230:231], off
	s_mov_b32 m0, s37
	v_lshl_add_u64 v[234:235], s[20:21], 0, v[162:163]
	global_load_lds_dwordx4 v[232:233], off
	s_mov_b32 m0, s40
	s_nop 0
	global_load_lds_dwordx4 v[234:235], off
	s_waitcnt vmcnt(8)
	s_waitcnt lgkmcnt(0)
	s_setprio 1
	s_barrier
; #define PG8_STAGE(bufoff, gbase, voff) do { _Pragma("unroll") for (int _i = 0; _i < 2; ++_i) \
;         __builtin_amdgcn_global_load_lds((const unsigned*)((const char*)(gbase) + (voff)[_i]), (LAS unsigned*)(lds + (bufoff) + ldsw + _i * 8192), 16, 0, 0); } while (0)
; #define PG8_LDA(dst, b, h) do { _Pragma("unroll") for (int m = 0; m < 4; ++m) _Pragma("unroll") for (int k = 0; k < 2; ++k) dst[m][k] = *(const LAS bf16x8*)(lds + PG8_SA(b, h) + aoff + m * 2048 + k * 1024); } while (0)
; #define PG8_LDB(dst, b, h) do { _Pragma("unroll") for (int n = 0; n < 2; ++n) _Pragma("unroll") for (int k = 0; k < 2; ++k) dst[n][k] = *(const LAS bf16x8*)(lds + PG8_SB(b, h) + boff + n * 2048 + k * 1024); } while (0)
; #define PG8_MMA(ai, bj, At, Bt) do { __builtin_amdgcn_s_setprio(1); _Pragma("unroll") for (int m = 0; m < 4; ++m) _Pragma("unroll") for (int n = 0; n < 2; ++n) _Pragma("unroll") for (int k = 0; k < 2; ++k) \
;         acc[ai][bj][m][n] = __builtin_amdgcn_mfma_f32_16x16x32_bf16(Bt[n][k], At[m][k], acc[ai][bj][m][n], 0, 0, 0); __builtin_amdgcn_s_setprio(0); } while (0)
; #define PG8_WAIT_V(n) asm volatile("s_waitcnt vmcnt(" #n ")" ::: "memory")
; #define PG8_WAIT_L(n) asm volatile("s_waitcnt lgkmcnt(" #n ")" ::: "memory")
; #define PG8_BAR __builtin_amdgcn_s_barrier()
; #define PG8_SCHED __builtin_amdgcn_sched_barrier(0)
; template <class Epi, class Sched>
; __device__ __forceinline__ void gemm_phase(LAS unsigned char* lds, const Gemm g, const Sched S, const Epi E, const int tid) {
;     ...
;             PG8_WAIT_V(8); PG8_WAIT_L(0); PG8_BAR; PG8_MMA(0, 0, At, B0); PG8_MMA(0, 1, At, B1); PG8_BAR; PG8_SCHED;
;             PG8_LDA(At, 0, 1); PG8_STAGE(PG8_SB(0, 0), b2, voffB); PG8_STAGE(PG8_SB(0, 1), b2 + hstepB, voffB); PG8_STAGE(PG8_SA(0, 0), a2, voffA);
;             PG8_WAIT_V(8); PG8_WAIT_L(0); PG8_BAR; PG8_MMA(1, 0, At, B0); PG8_MMA(1, 1, At, B1); PG8_BAR; PG8_SCHED;
;             PG8_LDB(B0, 1, 0); PG8_LDB(B1, 1, 1); PG8_SCHED; PG8_LDA(At, 1, 0); PG8_STAGE(PG8_SA(0, 1), a2 + hstepA, voffA);
;             PG8_WAIT_V(8); PG8_WAIT_L(0); PG8_BAR; PG8_MMA(0, 0, At, B0); PG8_MMA(0, 1, At, B1); PG8_BAR; PG8_SCHED;
	v_mfma_f32_16x16x32_bf16 v[62:65], v[126:129], v[190:193], v[62:65]
	v_mfma_f32_16x16x32_bf16 v[58:61], v[138:141], v[190:193], v[58:61]
	v_mfma_f32_16x16x32_bf16 v[46:49], v[126:129], v[200:203], v[46:49]
	v_mfma_f32_16x16x32_bf16 v[42:45], v[138:141], v[200:203], v[42:45]
	v_mfma_f32_16x16x32_bf16 v[30:33], v[126:129], v[208:211], v[30:33]
	v_mfma_f32_16x16x32_bf16 v[26:29], v[138:141], v[208:211], v[26:29]
	v_mfma_f32_16x16x32_bf16 v[14:17], v[126:129], v[216:219], v[14:17]
	v_mfma_f32_16x16x32_bf16 v[10:13], v[138:141], v[216:219], v[10:13]
	v_mfma_f32_16x16x32_bf16 v[62:65], v[134:137], v[194:197], v[62:65]
	v_mfma_f32_16x16x32_bf16 v[58:61], v[142:145], v[194:197], v[58:61]
	v_mfma_f32_16x16x32_bf16 v[46:49], v[134:137], v[204:207], v[46:49]
	v_mfma_f32_16x16x32_bf16 v[42:45], v[142:145], v[204:207], v[42:45]
	v_mfma_f32_16x16x32_bf16 v[30:33], v[134:137], v[212:215], v[30:33]
	v_mfma_f32_16x16x32_bf16 v[26:29], v[142:145], v[212:215], v[26:29]
	v_mfma_f32_16x16x32_bf16 v[14:17], v[134:137], v[220:223], v[14:17]
	v_mfma_f32_16x16x32_bf16 v[10:13], v[142:145], v[220:223], v[10:13]
	v_mfma_f32_16x16x32_bf16 v[54:57], v[146:149], v[190:193], v[54:57]
	v_mfma_f32_16x16x32_bf16 v[50:53], v[154:157], v[190:193], v[50:53]
	v_mfma_f32_16x16x32_bf16 v[38:41], v[146:149], v[200:203], v[38:41]
	v_mfma_f32_16x16x32_bf16 v[34:37], v[154:157], v[200:203], v[34:37]
	v_mfma_f32_16x16x32_bf16 v[22:25], v[146:149], v[208:211], v[22:25]
	v_mfma_f32_16x16x32_bf16 v[18:21], v[154:157], v[208:211], v[18:21]
	v_mfma_f32_16x16x32_bf16 v[6:9], v[146:149], v[216:219], v[6:9]
	v_mfma_f32_16x16x32_bf16 v[2:5], v[154:157], v[216:219], v[2:5]
	v_mfma_f32_16x16x32_bf16 v[54:57], v[150:153], v[194:197], v[54:57]
	v_mfma_f32_16x16x32_bf16 v[50:53], v[186:189], v[194:197], v[50:53]
	v_mfma_f32_16x16x32_bf16 v[38:41], v[150:153], v[204:207], v[38:41]
	v_mfma_f32_16x16x32_bf16 v[34:37], v[186:189], v[204:207], v[34:37]
	v_mfma_f32_16x16x32_bf16 v[22:25], v[150:153], v[212:215], v[22:25]
	v_mfma_f32_16x16x32_bf16 v[18:21], v[186:189], v[212:215], v[18:21]
	v_mfma_f32_16x16x32_bf16 v[6:9], v[150:153], v[220:223], v[6:9]
	v_mfma_f32_16x16x32_bf16 v[2:5], v[186:189], v[220:223], v[2:5]
	s_barrier
	s_setprio 0
	s_add_i32 s95, 0, 0x18000
	s_add_i32 s96, 0, 0x1c000
	v_add_u32_e32 v142, s95, v198
	v_add_u32_e32 v167, s96, v198
	ds_read_b128 v[126:129], v142
	ds_read_b128 v[134:137], v142 offset:1024
	ds_read_b128 v[138:141], v142 offset:2048
	ds_read_b128 v[142:145], v142 offset:3072
	ds_read_b128 v[146:149], v167
	ds_read_b128 v[150:153], v167 offset:1024
	ds_read_b128 v[154:157], v167 offset:2048
	ds_read_b128 v[186:189], v167 offset:3072
	s_add_u32 s20, s20, s62
	s_addc_u32 s21, s21, 0
	s_mov_b32 m0, s41
	v_lshl_add_u64 v[246:247], s[20:21], 0, v[158:159]
	ds_read_b128 v[190:193], v199 offset:32768
	ds_read_b128 v[194:197], v199 offset:33792
	ds_read_b128 v[200:203], v199 offset:34816
	ds_read_b128 v[204:207], v199 offset:35840
	ds_read_b128 v[208:211], v199 offset:36864
	ds_read_b128 v[212:215], v199 offset:37888
	ds_read_b128 v[216:219], v199 offset:38912
	ds_read_b128 v[220:223], v199 offset:39936
	global_load_lds_dwordx4 v[246:247], off
	v_lshl_add_u64 v[246:247], s[20:21], 0, v[162:163]
	s_mov_b32 m0, s42
	s_nop 0
	global_load_lds_dwordx4 v[246:247], off
	s_waitcnt vmcnt(8)
	s_waitcnt lgkmcnt(0)
	s_setprio 1
	s_barrier
	v_mfma_f32_16x16x32_bf16 v[130:133], v[126:129], v[190:193], v[130:133]
	v_mfma_f32_16x16x32_bf16 v[122:125], v[138:141], v[190:193], v[122:125]
	v_mfma_f32_16x16x32_bf16 v[110:113], v[126:129], v[200:203], v[110:113]
	v_mfma_f32_16x16x32_bf16 v[106:109], v[138:141], v[200:203], v[106:109]
	v_mfma_f32_16x16x32_bf16 v[94:97], v[126:129], v[208:211], v[94:97]
	v_mfma_f32_16x16x32_bf16 v[90:93], v[138:141], v[208:211], v[90:93]
	v_mfma_f32_16x16x32_bf16 v[78:81], v[126:129], v[216:219], v[78:81]
	v_mfma_f32_16x16x32_bf16 v[74:77], v[138:141], v[216:219], v[74:77]
	v_mfma_f32_16x16x32_bf16 v[130:133], v[134:137], v[194:197], v[130:133]
	v_mfma_f32_16x16x32_bf16 v[122:125], v[142:145], v[194:197], v[122:125]
	v_mfma_f32_16x16x32_bf16 v[110:113], v[134:137], v[204:207], v[110:113]
	v_mfma_f32_16x16x32_bf16 v[106:109], v[142:145], v[204:207], v[106:109]
	v_mfma_f32_16x16x32_bf16 v[94:97], v[134:137], v[212:215], v[94:97]
	v_mfma_f32_16x16x32_bf16 v[90:93], v[142:145], v[212:215], v[90:93]
	v_mfma_f32_16x16x32_bf16 v[78:81], v[134:137], v[220:223], v[78:81]
	v_mfma_f32_16x16x32_bf16 v[74:77], v[142:145], v[220:223], v[74:77]
	v_mfma_f32_16x16x32_bf16 v[118:121], v[146:149], v[190:193], v[118:121]
	v_mfma_f32_16x16x32_bf16 v[114:117], v[154:157], v[190:193], v[114:117]
	v_mfma_f32_16x16x32_bf16 v[102:105], v[146:149], v[200:203], v[102:105]
	v_mfma_f32_16x16x32_bf16 v[98:101], v[154:157], v[200:203], v[98:101]
	v_mfma_f32_16x16x32_bf16 v[86:89], v[146:149], v[208:211], v[86:89]
	v_mfma_f32_16x16x32_bf16 v[82:85], v[154:157], v[208:211], v[82:85]
	v_mfma_f32_16x16x32_bf16 v[70:73], v[146:149], v[216:219], v[70:73]
	v_mfma_f32_16x16x32_bf16 v[66:69], v[154:157], v[216:219], v[66:69]
	v_mfma_f32_16x16x32_bf16 v[118:121], v[150:153], v[194:197], v[118:121]
	v_mfma_f32_16x16x32_bf16 v[114:117], v[186:189], v[194:197], v[114:117]
	v_mfma_f32_16x16x32_bf16 v[102:105], v[150:153], v[204:207], v[102:105]
	v_mfma_f32_16x16x32_bf16 v[98:101], v[186:189], v[204:207], v[98:101]
	v_mfma_f32_16x16x32_bf16 v[86:89], v[150:153], v[212:215], v[86:89]
	v_mfma_f32_16x16x32_bf16 v[82:85], v[186:189], v[212:215], v[82:85]
	v_mfma_f32_16x16x32_bf16 v[70:73], v[150:153], v[220:223], v[70:73]
	v_mfma_f32_16x16x32_bf16 v[66:69], v[186:189], v[220:223], v[66:69]
	s_barrier
; #define PG8_STAGE(bufoff, gbase, voff) do { _Pragma("unroll") for (int _i = 0; _i < 2; ++_i) \
;         __builtin_amdgcn_global_load_lds((const unsigned*)((const char*)(gbase) + (voff)[_i]), (LAS unsigned*)(lds + (bufoff) + ldsw + _i * 8192), 16, 0, 0); } while (0)
; #define PG8_LDA(dst, b, h) do { _Pragma("unroll") for (int m = 0; m < 4; ++m) _Pragma("unroll") for (int k = 0; k < 2; ++k) dst[m][k] = *(const LAS bf16x8*)(lds + PG8_SA(b, h) + aoff + m * 2048 + k * 1024); } while (0)
; #define PG8_MMA(ai, bj, At, Bt) do { __builtin_amdgcn_s_setprio(1); _Pragma("unroll") for (int m = 0; m < 4; ++m) _Pragma("unroll") for (int n = 0; n < 2; ++n) _Pragma("unroll") for (int k = 0; k < 2; ++k) \
;         acc[ai][bj][m][n] = __builtin_amdgcn_mfma_f32_16x16x32_bf16(Bt[n][k], At[m][k], acc[ai][bj][m][n], 0, 0, 0); __builtin_amdgcn_s_setprio(0); } while (0)
; #define PG8_WAIT_V(n) asm volatile("s_waitcnt vmcnt(" #n ")" ::: "memory")
; #define PG8_WAIT_L(n) asm volatile("s_waitcnt lgkmcnt(" #n ")" ::: "memory")
; #define PG8_BAR __builtin_amdgcn_s_barrier()
; #define PG8_SCHED __builtin_amdgcn_sched_barrier(0)
; template <class Epi, class Sched>
; __device__ __forceinline__ void gemm_phase(LAS unsigned char* lds, const Gemm g, const Sched S, const Epi E, const int tid) {
;     ...
;             PG8_LDA(At, 1, 1); PG8_STAGE(PG8_SB(1, 0), b3, voffB); PG8_STAGE(PG8_SB(1, 1), b3 + hstepB, voffB); PG8_STAGE(PG8_SA(1, 0), a3, voffA);
;             PG8_WAIT_V(8); PG8_WAIT_L(0); PG8_BAR; PG8_MMA(1, 0, At, B0); PG8_MMA(1, 1, At, B1); PG8_BAR; PG8_SCHED;
;         }
;         if (wr == 0) PG8_BAR;
	s_setprio 0
	s_add_i32 s20, s95, s29
	v_lshl_add_u64 v[224:225], v[224:225], 0, s[64:65]
	s_mov_b32 m0, s20
	ds_read_b128 v[190:193], v199 offset:49152
	ds_read_b128 v[194:197], v199 offset:50176
	ds_read_b128 v[200:203], v199 offset:51200
	ds_read_b128 v[204:207], v199 offset:52224
	ds_read_b128 v[208:211], v199 offset:53248
	ds_read_b128 v[212:215], v199 offset:54272
	ds_read_b128 v[216:219], v199 offset:55296
	ds_read_b128 v[220:223], v199 offset:56320
	global_load_lds_dwordx4 v[224:225], off
	v_lshl_add_u64 v[224:225], v[226:227], 0, s[64:65]
	s_add_i32 m0, s20, 0x2000
	s_add_i32 s20, s96, s29
	global_load_lds_dwordx4 v[224:225], off
	v_lshl_add_u64 v[224:225], v[228:229], 0, s[64:65]
	s_mov_b32 m0, s20
	s_nop 0
	global_load_lds_dwordx4 v[224:225], off
	v_lshl_add_u64 v[224:225], v[230:231], 0, s[64:65]
	s_add_i32 m0, s20, 0x2000
	s_nop 0
	global_load_lds_dwordx4 v[224:225], off
	v_lshl_add_u64 v[224:225], v[232:233], 0, s[64:65]
	s_mov_b32 m0, s45
	s_nop 0
	global_load_lds_dwordx4 v[224:225], off
	v_lshl_add_u64 v[224:225], v[234:235], 0, s[64:65]
	s_mov_b32 m0, s46
	s_nop 0
	global_load_lds_dwordx4 v[224:225], off
	s_waitcnt vmcnt(8)
	s_waitcnt lgkmcnt(0)
	s_setprio 1
	s_barrier
	v_mfma_f32_16x16x32_bf16 v[62:65], v[126:129], v[190:193], v[62:65]
	v_mfma_f32_16x16x32_bf16 v[58:61], v[138:141], v[190:193], v[58:61]
	v_mfma_f32_16x16x32_bf16 v[46:49], v[126:129], v[200:203], v[46:49]
	v_mfma_f32_16x16x32_bf16 v[42:45], v[138:141], v[200:203], v[42:45]
	v_mfma_f32_16x16x32_bf16 v[30:33], v[126:129], v[208:211], v[30:33]
	v_mfma_f32_16x16x32_bf16 v[26:29], v[138:141], v[208:211], v[26:29]
	v_mfma_f32_16x16x32_bf16 v[14:17], v[126:129], v[216:219], v[14:17]
	v_mfma_f32_16x16x32_bf16 v[10:13], v[138:141], v[216:219], v[10:13]
	v_mfma_f32_16x16x32_bf16 v[62:65], v[134:137], v[194:197], v[62:65]
	v_mfma_f32_16x16x32_bf16 v[58:61], v[142:145], v[194:197], v[58:61]
	v_mfma_f32_16x16x32_bf16 v[46:49], v[134:137], v[204:207], v[46:49]
	v_mfma_f32_16x16x32_bf16 v[42:45], v[142:145], v[204:207], v[42:45]
	v_mfma_f32_16x16x32_bf16 v[30:33], v[134:137], v[212:215], v[30:33]
	v_mfma_f32_16x16x32_bf16 v[26:29], v[142:145], v[212:215], v[26:29]
	v_mfma_f32_16x16x32_bf16 v[14:17], v[134:137], v[220:223], v[14:17]
	v_mfma_f32_16x16x32_bf16 v[10:13], v[142:145], v[220:223], v[10:13]
	v_mfma_f32_16x16x32_bf16 v[54:57], v[146:149], v[190:193], v[54:57]
	v_mfma_f32_16x16x32_bf16 v[50:53], v[154:157], v[190:193], v[50:53]
	v_mfma_f32_16x16x32_bf16 v[38:41], v[146:149], v[200:203], v[38:41]
	v_mfma_f32_16x16x32_bf16 v[34:37], v[154:157], v[200:203], v[34:37]
	v_mfma_f32_16x16x32_bf16 v[22:25], v[146:149], v[208:211], v[22:25]
	v_mfma_f32_16x16x32_bf16 v[18:21], v[154:157], v[208:211], v[18:21]
	v_mfma_f32_16x16x32_bf16 v[6:9], v[146:149], v[216:219], v[6:9]
	v_mfma_f32_16x16x32_bf16 v[2:5], v[154:157], v[216:219], v[2:5]
	v_mfma_f32_16x16x32_bf16 v[54:57], v[150:153], v[194:197], v[54:57]
	v_mfma_f32_16x16x32_bf16 v[50:53], v[186:189], v[194:197], v[50:53]
	v_mfma_f32_16x16x32_bf16 v[38:41], v[150:153], v[204:207], v[38:41]
	v_mfma_f32_16x16x32_bf16 v[34:37], v[186:189], v[204:207], v[34:37]
	v_mfma_f32_16x16x32_bf16 v[22:25], v[150:153], v[212:215], v[22:25]
	v_mfma_f32_16x16x32_bf16 v[18:21], v[186:189], v[212:215], v[18:21]
	v_mfma_f32_16x16x32_bf16 v[6:9], v[150:153], v[220:223], v[6:9]
	v_mfma_f32_16x16x32_bf16 v[2:5], v[186:189], v[220:223], v[2:5]
	s_barrier
	s_setprio 0
	s_add_u32 s92, s92, 0x100
	s_addc_u32 s93, s93, 0
	s_add_u32 s18, s18, 0x100
	s_addc_u32 s19, s19, 0
	s_cmp_ge_u32 s94, s47
	s_mov_b32 s20, s94
	s_cbranch_scc0 .LBB0_778
	s_and_b64 vcc, exec, s[12:13]
	s_cbranch_vccz .LBB0_781
	s_barrier

; #define PG8_STAGE(bufoff, gbase, voff) do { _Pragma("unroll") for (int _i = 0; _i < 2; ++_i) \
;         __builtin_amdgcn_global_load_lds((const unsigned*)((const char*)(gbase) + (voff)[_i]), (LAS unsigned*)(lds + (bufoff) + ldsw + _i * 8192), 16, 0, 0); } while (0)
; #define PG8_LDA(dst, b, h) do { _Pragma("unroll") for (int m = 0; m < 4; ++m) _Pragma("unroll") for (int k = 0; k < 2; ++k) dst[m][k] = *(const LAS bf16x8*)(lds + PG8_SA(b, h) + aoff + m * 2048 + k * 1024); } while (0)
; #define PG8_LDB(dst, b, h) do { _Pragma("unroll") for (int n = 0; n < 2; ++n) _Pragma("unroll") for (int k = 0; k < 2; ++k) dst[n][k] = *(const LAS bf16x8*)(lds + PG8_SB(b, h) + boff + n * 2048 + k * 1024); } while (0)
; #define PG8_WAIT_V(n) asm volatile("s_waitcnt vmcnt(" #n ")" ::: "memory")
; #define PG8_BAR __builtin_amdgcn_s_barrier()
; template <class Epi, class Sched>
; __device__ __forceinline__ void gemm_phase(LAS unsigned char* lds, const Gemm g, const Sched S, const Epi E, const int tid) {
;     ...
;         for (int t = 0; t < nt; t += 2) {
;             const bool last = (t == nt - 2);
;             const char* a1 = cA + (size_t)(t + 1) * kstep;
;             const char* a2 = last ? nA : cA + (size_t)(t + 2) * kstep; const char* b2 = last ? nB : cB + (size_t)(t + 2) * kstep;
;             const char* a3 = a2 + kstep; const char* b3 = b2 + kstep;
;             PG8_LDB(B0, 0, 0); PG8_LDB(B1, 0, 1); PG8_SCHED; PG8_LDA(At, 0, 0); PG8_STAGE(PG8_SA(1, 1), a1 + hstepA, voffA);
;             PG8_WAIT_V(8); PG8_WAIT_L(0); PG8_BAR; PG8_MMA(0, 0, At, B0); PG8_MMA(0, 1, At, B1); PG8_BAR; PG8_SCHED;
;             PG8_LDA(At, 0, 1); PG8_STAGE(PG8_SB(0, 0), b2, voffB); PG8_STAGE(PG8_SB(0, 1), b2 + hstepB, voffB); PG8_STAGE(PG8_SA(0, 0), a2, voffA);
;             PG8_WAIT_V(8); PG8_WAIT_L(0); PG8_BAR; PG8_MMA(1, 0, At, B0); PG8_MMA(1, 1, At, B1); PG8_BAR; PG8_SCHED;
;             PG8_LDB(B0, 1, 0); PG8_LDB(B1, 1, 1); PG8_SCHED; PG8_LDA(At, 1, 0); PG8_STAGE(PG8_SA(0, 1), a2 + hstepA, voffA);
;             PG8_WAIT_V(8); PG8_WAIT_L(0); PG8_BAR; PG8_MMA(0, 0, At, B0); PG8_MMA(0, 1, At, B1); PG8_BAR; PG8_SCHED;
;             PG8_LDA(At, 1, 1); PG8_STAGE(PG8_SB(1, 0), b3, voffB); PG8_STAGE(PG8_SB(1, 1), b3 + hstepB, voffB); PG8_STAGE(PG8_SA(1, 0), a3, voffA);
;             PG8_WAIT_V(8); PG8_WAIT_L(0); PG8_BAR; PG8_MMA(1, 0, At, B0); PG8_MMA(1, 1, At, B1); PG8_BAR; PG8_SCHED;
.LBB0_819:
	s_add_u32 s24, s22, 0xfffc0080
	s_addc_u32 s25, s23, -1
	s_add_i32 s85, 0, 0x10000
	s_cmp_eq_u32 s84, 12
	s_cselect_b32 s27, s9, s25
	s_cselect_b32 s26, s17, s24
	s_cselect_b32 s25, s15, s83
	s_cselect_b32 s24, s69, s82
	s_add_i32 s90, 0, 0x14000
	v_add_u32_e32 v154, s85, v165
	v_add_u32_e32 v162, s90, v165
	ds_read_b128 v[98:101], v154
	ds_read_b128 v[134:137], v154 offset:1024
	ds_read_b128 v[150:153], v154 offset:2048
	ds_read_b128 v[154:157], v154 offset:3072
	ds_read_b128 v[158:161], v162
	ds_read_b128 v[180:183], v162 offset:1024
	ds_read_b128 v[184:187], v162 offset:2048
	ds_read_b128 v[188:191], v162 offset:3072
	v_lshl_add_u64 v[162:163], s[22:23], 0, v[148:149]
	s_add_i32 m0, s40, 0xc000
	ds_read_b128 v[192:195], v166
	ds_read_b128 v[196:199], v166 offset:1024
	ds_read_b128 v[200:203], v166 offset:2048
	ds_read_b128 v[204:207], v166 offset:3072
	ds_read_b128 v[208:211], v166 offset:4096
	ds_read_b128 v[212:215], v166 offset:5120
	ds_read_b128 v[216:219], v166 offset:6144
	ds_read_b128 v[220:223], v166 offset:7168
	global_load_lds_dwordx4 v[162:163], off
	v_lshl_add_u64 v[162:163], s[22:23], 0, v[146:147]
	s_add_i32 m0, s40, 0xe000
	s_nop 0
	global_load_lds_dwordx4 v[162:163], off
	s_waitcnt vmcnt(8)
	s_waitcnt lgkmcnt(0)
	s_setprio 1
	s_barrier
	v_mfma_f32_16x16x32_bf16 v[130:133], v[98:101], v[192:195], v[130:133]
	v_mfma_f32_16x16x32_bf16 v[118:121], v[150:153], v[192:195], v[118:121]
	v_mfma_f32_16x16x32_bf16 v[114:117], v[98:101], v[200:203], v[114:117]
	v_mfma_f32_16x16x32_bf16 v[102:105], v[150:153], v[200:203], v[102:105]
	v_mfma_f32_16x16x32_bf16 v[94:97], v[98:101], v[208:211], v[94:97]
	v_mfma_f32_16x16x32_bf16 v[82:85], v[150:153], v[208:211], v[82:85]
	v_mfma_f32_16x16x32_bf16 v[78:81], v[98:101], v[216:219], v[78:81]
	v_mfma_f32_16x16x32_bf16 v[66:69], v[150:153], v[216:219], v[66:69]
	v_mfma_f32_16x16x32_bf16 v[130:133], v[134:137], v[196:199], v[130:133]
	v_mfma_f32_16x16x32_bf16 v[118:121], v[154:157], v[196:199], v[118:121]
	v_mfma_f32_16x16x32_bf16 v[114:117], v[134:137], v[204:207], v[114:117]
	v_mfma_f32_16x16x32_bf16 v[102:105], v[154:157], v[204:207], v[102:105]
	v_mfma_f32_16x16x32_bf16 v[94:97], v[134:137], v[212:215], v[94:97]
	v_mfma_f32_16x16x32_bf16 v[82:85], v[154:157], v[212:215], v[82:85]
	v_mfma_f32_16x16x32_bf16 v[78:81], v[134:137], v[220:223], v[78:81]
	v_mfma_f32_16x16x32_bf16 v[66:69], v[154:157], v[220:223], v[66:69]
	v_mfma_f32_16x16x32_bf16 v[126:129], v[158:161], v[192:195], v[126:129]
	v_mfma_f32_16x16x32_bf16 v[122:125], v[184:187], v[192:195], v[122:125]
	v_mfma_f32_16x16x32_bf16 v[110:113], v[158:161], v[200:203], v[110:113]
	v_mfma_f32_16x16x32_bf16 v[106:109], v[184:187], v[200:203], v[106:109]
	v_mfma_f32_16x16x32_bf16 v[90:93], v[158:161], v[208:211], v[90:93]
	v_mfma_f32_16x16x32_bf16 v[86:89], v[184:187], v[208:211], v[86:89]
	v_mfma_f32_16x16x32_bf16 v[74:77], v[158:161], v[216:219], v[74:77]
	v_mfma_f32_16x16x32_bf16 v[70:73], v[184:187], v[216:219], v[70:73]
	v_mfma_f32_16x16x32_bf16 v[126:129], v[180:183], v[196:199], v[126:129]
	v_mfma_f32_16x16x32_bf16 v[122:125], v[188:191], v[196:199], v[122:125]
	v_mfma_f32_16x16x32_bf16 v[110:113], v[180:183], v[204:207], v[110:113]
	v_mfma_f32_16x16x32_bf16 v[106:109], v[188:191], v[204:207], v[106:109]
	v_mfma_f32_16x16x32_bf16 v[90:93], v[180:183], v[212:215], v[90:93]
	v_mfma_f32_16x16x32_bf16 v[86:89], v[188:191], v[212:215], v[86:89]
	v_mfma_f32_16x16x32_bf16 v[74:77], v[180:183], v[220:223], v[74:77]
	v_mfma_f32_16x16x32_bf16 v[70:73], v[188:191], v[220:223], v[70:73]
	s_barrier
	s_setprio 0
	s_add_i32 s85, s85, s28
	v_lshl_add_u64 v[162:163], s[24:25], 0, v[142:143]
	s_mov_b32 m0, s85
	ds_read_b128 v[192:195], v166 offset:16384
	ds_read_b128 v[196:199], v166 offset:17408
	ds_read_b128 v[200:203], v166 offset:18432
	ds_read_b128 v[204:207], v166 offset:19456
	ds_read_b128 v[208:211], v166 offset:20480
	ds_read_b128 v[212:215], v166 offset:21504
	ds_read_b128 v[216:219], v166 offset:22528
	ds_read_b128 v[220:223], v166 offset:23552
	global_load_lds_dwordx4 v[162:163], off
	s_add_i32 m0, s85, 0x2000
	s_add_u32 s88, s24, 0x40000
	v_lshl_add_u64 v[224:225], s[24:25], 0, v[138:139]
	s_addc_u32 s89, s25, 0
	s_add_i32 s85, s90, s28
	global_load_lds_dwordx4 v[224:225], off
	v_lshl_add_u64 v[226:227], s[88:89], 0, v[142:143]
	s_mov_b32 m0, s85
	v_lshl_add_u64 v[228:229], s[26:27], 0, v[140:141]
	global_load_lds_dwordx4 v[226:227], off
	v_lshl_add_u64 v[226:227], s[88:89], 0, v[138:139]
	s_add_i32 m0, s85, 0x2000
	s_nop 0
	global_load_lds_dwordx4 v[226:227], off
	v_lshl_add_u64 v[226:227], s[26:27], 0, v[144:145]
	s_mov_b32 m0, s40
	s_nop 0
	global_load_lds_dwordx4 v[226:227], off
	s_mov_b32 m0, s41
	s_nop 0
	global_load_lds_dwordx4 v[228:229], off
	s_waitcnt vmcnt(8)
	s_waitcnt lgkmcnt(0)
	s_setprio 1
	s_barrier
; #define PG8_STAGE(bufoff, gbase, voff) do { _Pragma("unroll") for (int _i = 0; _i < 2; ++_i) \
;         __builtin_amdgcn_global_load_lds((const unsigned*)((const char*)(gbase) + (voff)[_i]), (LAS unsigned*)(lds + (bufoff) + ldsw + _i * 8192), 16, 0, 0); } while (0)
; #define PG8_LDA(dst, b, h) do { _Pragma("unroll") for (int m = 0; m < 4; ++m) _Pragma("unroll") for (int k = 0; k < 2; ++k) dst[m][k] = *(const LAS bf16x8*)(lds + PG8_SA(b, h) + aoff + m * 2048 + k * 1024); } while (0)
; #define PG8_LDB(dst, b, h) do { _Pragma("unroll") for (int n = 0; n < 2; ++n) _Pragma("unroll") for (int k = 0; k < 2; ++k) dst[n][k] = *(const LAS bf16x8*)(lds + PG8_SB(b, h) + boff + n * 2048 + k * 1024); } while (0)
; #define PG8_MMA(ai, bj, At, Bt) do { __builtin_amdgcn_s_setprio(1); _Pragma("unroll") for (int m = 0; m < 4; ++m) _Pragma("unroll") for (int n = 0; n < 2; ++n) _Pragma("unroll") for (int k = 0; k < 2; ++k) \
;         acc[ai][bj][m][n] = __builtin_amdgcn_mfma_f32_16x16x32_bf16(Bt[n][k], At[m][k], acc[ai][bj][m][n], 0, 0, 0); __builtin_amdgcn_s_setprio(0); } while (0)
; #define PG8_WAIT_V(n) asm volatile("s_waitcnt vmcnt(" #n ")" ::: "memory")
; #define PG8_WAIT_L(n) asm volatile("s_waitcnt lgkmcnt(" #n ")" ::: "memory")
; #define PG8_BAR __builtin_amdgcn_s_barrier()
; #define PG8_SCHED __builtin_amdgcn_sched_barrier(0)
; template <class Epi, class Sched>
; __device__ __forceinline__ void gemm_phase(LAS unsigned char* lds, const Gemm g, const Sched S, const Epi E, const int tid) {
;     ...
;             PG8_WAIT_V(8); PG8_WAIT_L(0); PG8_BAR; PG8_MMA(0, 0, At, B0); PG8_MMA(0, 1, At, B1); PG8_BAR; PG8_SCHED;
;             PG8_LDA(At, 0, 1); PG8_STAGE(PG8_SB(0, 0), b2, voffB); PG8_STAGE(PG8_SB(0, 1), b2 + hstepB, voffB); PG8_STAGE(PG8_SA(0, 0), a2, voffA);
;             PG8_WAIT_V(8); PG8_WAIT_L(0); PG8_BAR; PG8_MMA(1, 0, At, B0); PG8_MMA(1, 1, At, B1); PG8_BAR; PG8_SCHED;
;             PG8_LDB(B0, 1, 0); PG8_LDB(B1, 1, 1); PG8_SCHED; PG8_LDA(At, 1, 0); PG8_STAGE(PG8_SA(0, 1), a2 + hstepA, voffA);
;             PG8_WAIT_V(8); PG8_WAIT_L(0); PG8_BAR; PG8_MMA(0, 0, At, B0); PG8_MMA(0, 1, At, B1); PG8_BAR; PG8_SCHED;
	v_mfma_f32_16x16x32_bf16 v[62:65], v[98:101], v[192:195], v[62:65]
	v_mfma_f32_16x16x32_bf16 v[50:53], v[150:153], v[192:195], v[50:53]
	v_mfma_f32_16x16x32_bf16 v[46:49], v[98:101], v[200:203], v[46:49]
	v_mfma_f32_16x16x32_bf16 v[34:37], v[150:153], v[200:203], v[34:37]
	v_mfma_f32_16x16x32_bf16 v[30:33], v[98:101], v[208:211], v[30:33]
	v_mfma_f32_16x16x32_bf16 v[18:21], v[150:153], v[208:211], v[18:21]
	v_mfma_f32_16x16x32_bf16 v[14:17], v[98:101], v[216:219], v[14:17]
	v_mfma_f32_16x16x32_bf16 v[6:9], v[150:153], v[216:219], v[6:9]
	v_mfma_f32_16x16x32_bf16 v[62:65], v[134:137], v[196:199], v[62:65]
	v_mfma_f32_16x16x32_bf16 v[50:53], v[154:157], v[196:199], v[50:53]
	v_mfma_f32_16x16x32_bf16 v[46:49], v[134:137], v[204:207], v[46:49]
	v_mfma_f32_16x16x32_bf16 v[34:37], v[154:157], v[204:207], v[34:37]
	v_mfma_f32_16x16x32_bf16 v[30:33], v[134:137], v[212:215], v[30:33]
	v_mfma_f32_16x16x32_bf16 v[18:21], v[154:157], v[212:215], v[18:21]
	v_mfma_f32_16x16x32_bf16 v[14:17], v[134:137], v[220:223], v[14:17]
	v_mfma_f32_16x16x32_bf16 v[6:9], v[154:157], v[220:223], v[6:9]
	v_mfma_f32_16x16x32_bf16 v[58:61], v[158:161], v[192:195], v[58:61]
	v_mfma_f32_16x16x32_bf16 v[54:57], v[184:187], v[192:195], v[54:57]
	v_mfma_f32_16x16x32_bf16 v[42:45], v[158:161], v[200:203], v[42:45]
	v_mfma_f32_16x16x32_bf16 v[38:41], v[184:187], v[200:203], v[38:41]
	v_mfma_f32_16x16x32_bf16 v[26:29], v[158:161], v[208:211], v[26:29]
	v_mfma_f32_16x16x32_bf16 v[22:25], v[184:187], v[208:211], v[22:25]
	v_mfma_f32_16x16x32_bf16 v[10:13], v[158:161], v[216:219], v[10:13]
	v_mfma_f32_16x16x32_bf16 v[2:5], v[184:187], v[216:219], v[2:5]
	v_mfma_f32_16x16x32_bf16 v[58:61], v[180:183], v[196:199], v[58:61]
	v_mfma_f32_16x16x32_bf16 v[54:57], v[188:191], v[196:199], v[54:57]
	v_mfma_f32_16x16x32_bf16 v[42:45], v[180:183], v[204:207], v[42:45]
	v_mfma_f32_16x16x32_bf16 v[38:41], v[188:191], v[204:207], v[38:41]
	v_mfma_f32_16x16x32_bf16 v[26:29], v[180:183], v[212:215], v[26:29]
	v_mfma_f32_16x16x32_bf16 v[22:25], v[188:191], v[212:215], v[22:25]
	v_mfma_f32_16x16x32_bf16 v[10:13], v[180:183], v[220:223], v[10:13]
	v_mfma_f32_16x16x32_bf16 v[2:5], v[188:191], v[220:223], v[2:5]
	s_barrier
	s_setprio 0
	s_add_i32 s85, 0, 0x18000
	s_add_i32 s88, 0, 0x1c000
	v_add_u32_e32 v154, s85, v165
	v_add_u32_e32 v167, s88, v165
	ds_read_b128 v[98:101], v154
	ds_read_b128 v[134:137], v154 offset:1024
	ds_read_b128 v[150:153], v154 offset:2048
	ds_read_b128 v[154:157], v154 offset:3072
	ds_read_b128 v[158:161], v167
	ds_read_b128 v[180:183], v167 offset:1024
	ds_read_b128 v[184:187], v167 offset:2048
	ds_read_b128 v[188:191], v167 offset:3072
	s_add_u32 s26, s26, 0x40000
	s_addc_u32 s27, s27, 0
	s_mov_b32 m0, s42
	v_lshl_add_u64 v[230:231], s[26:27], 0, v[144:145]
	ds_read_b128 v[192:195], v166 offset:32768
	ds_read_b128 v[196:199], v166 offset:33792
	ds_read_b128 v[200:203], v166 offset:34816
	ds_read_b128 v[204:207], v166 offset:35840
	ds_read_b128 v[208:211], v166 offset:36864
	ds_read_b128 v[212:215], v166 offset:37888
	ds_read_b128 v[216:219], v166 offset:38912
	ds_read_b128 v[220:223], v166 offset:39936
	global_load_lds_dwordx4 v[230:231], off
	v_lshl_add_u64 v[230:231], s[26:27], 0, v[140:141]
	s_mov_b32 m0, s43
	s_nop 0
	global_load_lds_dwordx4 v[230:231], off
	s_waitcnt vmcnt(8)
	s_waitcnt lgkmcnt(0)
	s_setprio 1
	s_barrier
	v_mfma_f32_16x16x32_bf16 v[130:133], v[98:101], v[192:195], v[130:133]
	v_mfma_f32_16x16x32_bf16 v[118:121], v[150:153], v[192:195], v[118:121]
	v_mfma_f32_16x16x32_bf16 v[114:117], v[98:101], v[200:203], v[114:117]
	v_mfma_f32_16x16x32_bf16 v[102:105], v[150:153], v[200:203], v[102:105]
	v_mfma_f32_16x16x32_bf16 v[94:97], v[98:101], v[208:211], v[94:97]
	v_mfma_f32_16x16x32_bf16 v[82:85], v[150:153], v[208:211], v[82:85]
	v_mfma_f32_16x16x32_bf16 v[78:81], v[98:101], v[216:219], v[78:81]
	v_mfma_f32_16x16x32_bf16 v[66:69], v[150:153], v[216:219], v[66:69]
	v_mfma_f32_16x16x32_bf16 v[130:133], v[134:137], v[196:199], v[130:133]
	v_mfma_f32_16x16x32_bf16 v[118:121], v[154:157], v[196:199], v[118:121]
	v_mfma_f32_16x16x32_bf16 v[114:117], v[134:137], v[204:207], v[114:117]
	v_mfma_f32_16x16x32_bf16 v[102:105], v[154:157], v[204:207], v[102:105]
	v_mfma_f32_16x16x32_bf16 v[94:97], v[134:137], v[212:215], v[94:97]
	v_mfma_f32_16x16x32_bf16 v[82:85], v[154:157], v[212:215], v[82:85]
	v_mfma_f32_16x16x32_bf16 v[78:81], v[134:137], v[220:223], v[78:81]
	v_mfma_f32_16x16x32_bf16 v[66:69], v[154:157], v[220:223], v[66:69]
	v_mfma_f32_16x16x32_bf16 v[126:129], v[158:161], v[192:195], v[126:129]
	v_mfma_f32_16x16x32_bf16 v[122:125], v[184:187], v[192:195], v[122:125]
	v_mfma_f32_16x16x32_bf16 v[110:113], v[158:161], v[200:203], v[110:113]
	v_mfma_f32_16x16x32_bf16 v[106:109], v[184:187], v[200:203], v[106:109]
	v_mfma_f32_16x16x32_bf16 v[90:93], v[158:161], v[208:211], v[90:93]
	v_mfma_f32_16x16x32_bf16 v[86:89], v[184:187], v[208:211], v[86:89]
	v_mfma_f32_16x16x32_bf16 v[74:77], v[158:161], v[216:219], v[74:77]
	v_mfma_f32_16x16x32_bf16 v[70:73], v[184:187], v[216:219], v[70:73]
	v_mfma_f32_16x16x32_bf16 v[126:129], v[180:183], v[196:199], v[126:129]
	v_mfma_f32_16x16x32_bf16 v[122:125], v[188:191], v[196:199], v[122:125]
	v_mfma_f32_16x16x32_bf16 v[110:113], v[180:183], v[204:207], v[110:113]
	v_mfma_f32_16x16x32_bf16 v[106:109], v[188:191], v[204:207], v[106:109]
	v_mfma_f32_16x16x32_bf16 v[90:93], v[180:183], v[212:215], v[90:93]
	v_mfma_f32_16x16x32_bf16 v[86:89], v[188:191], v[212:215], v[86:89]
	v_mfma_f32_16x16x32_bf16 v[74:77], v[180:183], v[220:223], v[74:77]
	v_mfma_f32_16x16x32_bf16 v[70:73], v[188:191], v[220:223], v[70:73]
	s_barrier
; #define PG8_STAGE(bufoff, gbase, voff) do { _Pragma("unroll") for (int _i = 0; _i < 2; ++_i) \
;         __builtin_amdgcn_global_load_lds((const unsigned*)((const char*)(gbase) + (voff)[_i]), (LAS unsigned*)(lds + (bufoff) + ldsw + _i * 8192), 16, 0, 0); } while (0)
; #define PG8_LDA(dst, b, h) do { _Pragma("unroll") for (int m = 0; m < 4; ++m) _Pragma("unroll") for (int k = 0; k < 2; ++k) dst[m][k] = *(const LAS bf16x8*)(lds + PG8_SA(b, h) + aoff + m * 2048 + k * 1024); } while (0)
; #define PG8_MMA(ai, bj, At, Bt) do { __builtin_amdgcn_s_setprio(1); _Pragma("unroll") for (int m = 0; m < 4; ++m) _Pragma("unroll") for (int n = 0; n < 2; ++n) _Pragma("unroll") for (int k = 0; k < 2; ++k) \
;         acc[ai][bj][m][n] = __builtin_amdgcn_mfma_f32_16x16x32_bf16(Bt[n][k], At[m][k], acc[ai][bj][m][n], 0, 0, 0); __builtin_amdgcn_s_setprio(0); } while (0)
; #define PG8_WAIT_V(n) asm volatile("s_waitcnt vmcnt(" #n ")" ::: "memory")
; #define PG8_WAIT_L(n) asm volatile("s_waitcnt lgkmcnt(" #n ")" ::: "memory")
; #define PG8_BAR __builtin_amdgcn_s_barrier()
; #define PG8_SCHED __builtin_amdgcn_sched_barrier(0)
; template <class Epi, class Sched>
; __device__ __forceinline__ void gemm_phase(LAS unsigned char* lds, const Gemm g, const Sched S, const Epi E, const int tid) {
;     ...
;             PG8_LDA(At, 1, 1); PG8_STAGE(PG8_SB(1, 0), b3, voffB); PG8_STAGE(PG8_SB(1, 1), b3 + hstepB, voffB); PG8_STAGE(PG8_SA(1, 0), a3, voffA);
;             PG8_WAIT_V(8); PG8_WAIT_L(0); PG8_BAR; PG8_MMA(1, 0, At, B0); PG8_MMA(1, 1, At, B1); PG8_BAR; PG8_SCHED;
;         }
;         if (wr == 0) PG8_BAR;
	s_setprio 0
	s_add_i32 s26, s85, s28
	v_lshl_add_u64 v[162:163], v[162:163], 0, s[64:65]
	s_mov_b32 m0, s26
	ds_read_b128 v[192:195], v166 offset:49152
	ds_read_b128 v[196:199], v166 offset:50176
	ds_read_b128 v[200:203], v166 offset:51200
	ds_read_b128 v[204:207], v166 offset:52224
	ds_read_b128 v[208:211], v166 offset:53248
	ds_read_b128 v[212:215], v166 offset:54272
	ds_read_b128 v[216:219], v166 offset:55296
	ds_read_b128 v[220:223], v166 offset:56320
	global_load_lds_dwordx4 v[162:163], off
	s_add_i32 m0, s26, 0x2000
	s_add_u32 s24, s24, 0x40080
	v_lshl_add_u64 v[162:163], v[224:225], 0, s[64:65]
	s_addc_u32 s25, s25, 0
	s_add_i32 s26, s88, s28
	global_load_lds_dwordx4 v[162:163], off
	v_lshl_add_u64 v[162:163], s[24:25], 0, v[142:143]
	s_mov_b32 m0, s26
	s_nop 0
	global_load_lds_dwordx4 v[162:163], off
	v_lshl_add_u64 v[162:163], s[24:25], 0, v[138:139]
	s_add_i32 m0, s26, 0x2000
	s_nop 0
	global_load_lds_dwordx4 v[162:163], off
	v_lshl_add_u64 v[162:163], v[226:227], 0, s[64:65]
	s_mov_b32 m0, s46
	s_nop 0
	global_load_lds_dwordx4 v[162:163], off
	v_lshl_add_u64 v[162:163], v[228:229], 0, s[64:65]
	s_mov_b32 m0, s47
	s_nop 0
	global_load_lds_dwordx4 v[162:163], off
	s_waitcnt vmcnt(8)
	s_waitcnt lgkmcnt(0)
	s_setprio 1
	s_barrier
	v_mfma_f32_16x16x32_bf16 v[62:65], v[98:101], v[192:195], v[62:65]
	v_mfma_f32_16x16x32_bf16 v[50:53], v[150:153], v[192:195], v[50:53]
	v_mfma_f32_16x16x32_bf16 v[46:49], v[98:101], v[200:203], v[46:49]
	v_mfma_f32_16x16x32_bf16 v[34:37], v[150:153], v[200:203], v[34:37]
	v_mfma_f32_16x16x32_bf16 v[30:33], v[98:101], v[208:211], v[30:33]
	v_mfma_f32_16x16x32_bf16 v[18:21], v[150:153], v[208:211], v[18:21]
	v_mfma_f32_16x16x32_bf16 v[14:17], v[98:101], v[216:219], v[14:17]
	v_mfma_f32_16x16x32_bf16 v[6:9], v[150:153], v[216:219], v[6:9]
	v_mfma_f32_16x16x32_bf16 v[62:65], v[134:137], v[196:199], v[62:65]
	v_mfma_f32_16x16x32_bf16 v[50:53], v[154:157], v[196:199], v[50:53]
	v_mfma_f32_16x16x32_bf16 v[46:49], v[134:137], v[204:207], v[46:49]
	v_mfma_f32_16x16x32_bf16 v[34:37], v[154:157], v[204:207], v[34:37]
	v_mfma_f32_16x16x32_bf16 v[30:33], v[134:137], v[212:215], v[30:33]
	v_mfma_f32_16x16x32_bf16 v[18:21], v[154:157], v[212:215], v[18:21]
	v_mfma_f32_16x16x32_bf16 v[14:17], v[134:137], v[220:223], v[14:17]
	v_mfma_f32_16x16x32_bf16 v[6:9], v[154:157], v[220:223], v[6:9]
	v_mfma_f32_16x16x32_bf16 v[58:61], v[158:161], v[192:195], v[58:61]
	v_mfma_f32_16x16x32_bf16 v[54:57], v[184:187], v[192:195], v[54:57]
	v_mfma_f32_16x16x32_bf16 v[42:45], v[158:161], v[200:203], v[42:45]
	v_mfma_f32_16x16x32_bf16 v[38:41], v[184:187], v[200:203], v[38:41]
	v_mfma_f32_16x16x32_bf16 v[26:29], v[158:161], v[208:211], v[26:29]
	v_mfma_f32_16x16x32_bf16 v[22:25], v[184:187], v[208:211], v[22:25]
	v_mfma_f32_16x16x32_bf16 v[10:13], v[158:161], v[216:219], v[10:13]
	v_mfma_f32_16x16x32_bf16 v[2:5], v[184:187], v[216:219], v[2:5]
	v_mfma_f32_16x16x32_bf16 v[58:61], v[180:183], v[196:199], v[58:61]
	v_mfma_f32_16x16x32_bf16 v[54:57], v[188:191], v[196:199], v[54:57]
	v_mfma_f32_16x16x32_bf16 v[42:45], v[180:183], v[204:207], v[42:45]
	v_mfma_f32_16x16x32_bf16 v[38:41], v[188:191], v[204:207], v[38:41]
	v_mfma_f32_16x16x32_bf16 v[26:29], v[180:183], v[212:215], v[26:29]
	v_mfma_f32_16x16x32_bf16 v[22:25], v[188:191], v[212:215], v[22:25]
	v_mfma_f32_16x16x32_bf16 v[10:13], v[180:183], v[220:223], v[10:13]
	v_mfma_f32_16x16x32_bf16 v[2:5], v[188:191], v[220:223], v[2:5]
	s_barrier
	s_setprio 0
	s_add_i32 s84, s84, 2
	s_add_u32 s82, s82, 0x100
	s_addc_u32 s83, s83, 0
	s_add_u32 s22, s22, 0x100
	s_addc_u32 s23, s23, 0
	s_cmp_gt_u32 s84, 13
	s_cbranch_scc0 .LBB0_819
	s_and_b64 vcc, exec, s[12:13]
	s_cbranch_vccz .LBB0_822
	s_barrier
